# v81 + peel: first K-loop body of P1/S3/S4/S5 units peeled, first MFMA per accumulator tile takes C=0, the 64 v_mov_b64 zeroing per unit removed
# speedup vs baseline: 1.0037x; 1.0037x over previous
.LBB0_367:
	s_ashr_i32 s55, s54, 31
	s_lshl_b64 s[2:3], s[54:55], 19
	s_add_u32 s58, s4, s2
	s_addc_u32 s59, s5, s3
	s_and_b64 s[2:3], s[56:57], exec
	s_cselect_b32 s2, s59, s7
	s_cselect_b32 s3, s58, s6
	s_ashr_i32 s53, s52, 31
	s_lshl_b64 s[10:11], s[52:53], 19
	s_add_u32 s60, s15, s10
	s_addc_u32 s61, s78, s11
	s_and_b64 s[10:11], s[56:57], exec
	s_cselect_b32 s12, s61, s9
	s_cselect_b32 s13, s60, s8
	s_add_u32 s6, s6, 0x40080
	s_addc_u32 s7, s7, 0
	s_add_u32 s24, s8, 0x100
	s_addc_u32 s25, s9, 0
	s_mov_b32 s26, -2
	ds_read_b128 v[114:117], v197
	ds_read_b128 v[134:137], v197 offset:1024
	ds_read_b128 v[138:141], v197 offset:2048
	ds_read_b128 v[142:145], v197 offset:3072
	ds_read_b128 v[146:149], v198
	ds_read_b128 v[150:153], v198 offset:1024
	ds_read_b128 v[154:157], v198 offset:2048
	ds_read_b128 v[158:161], v198 offset:3072
	s_add_u32 s0, s6, 0xfffc0080
	s_addc_u32 s8, s7, -1
	s_cmp_eq_u32 s26, 12
	s_cselect_b32 s11, s2, s8
	s_cselect_b32 s10, s3, s0
	s_cselect_b32 s9, s12, s25
	s_cselect_b32 s8, s13, s24
	s_add_i32 m0, s31, 0xc000
	ds_read_b128 v[184:187], v199
	ds_read_b128 v[188:191], v199 offset:1024
	ds_read_b128 v[206:209], v199 offset:2048
	ds_read_b128 v[210:213], v199 offset:3072
	ds_read_b128 v[214:217], v199 offset:4096
	ds_read_b128 v[218:221], v199 offset:5120
	ds_read_b128 v[222:225], v199 offset:6144
	ds_read_b128 v[226:229], v199 offset:7168
	global_load_lds_dwordx4 v180, s[6:7]
	s_add_i32 m0, s31, 0xe000
	s_nop 0
	global_load_lds_dwordx4 v182, s[6:7]
	s_waitcnt vmcnt(8)
	s_waitcnt lgkmcnt(0)
	s_barrier
	s_setprio 1
	s_waitcnt lgkmcnt(0)
	v_mfma_f32_16x16x32_bf16 v[130:133], v[114:117], v[184:187], 0
	v_mfma_f32_16x16x32_bf16 v[126:129], v[138:141], v[184:187], 0
	v_mfma_f32_16x16x32_bf16 v[110:113], v[114:117], v[206:209], 0
	v_mfma_f32_16x16x32_bf16 v[106:109], v[138:141], v[206:209], 0
	v_mfma_f32_16x16x32_bf16 v[94:97], v[114:117], v[214:217], 0
	v_mfma_f32_16x16x32_bf16 v[90:93], v[138:141], v[214:217], 0
	v_mfma_f32_16x16x32_bf16 v[78:81], v[114:117], v[222:225], 0
	v_mfma_f32_16x16x32_bf16 v[74:77], v[138:141], v[222:225], 0
	v_mfma_f32_16x16x32_bf16 v[130:133], v[134:137], v[188:191], v[130:133]
	v_mfma_f32_16x16x32_bf16 v[126:129], v[142:145], v[188:191], v[126:129]
	v_mfma_f32_16x16x32_bf16 v[110:113], v[134:137], v[210:213], v[110:113]
	v_mfma_f32_16x16x32_bf16 v[106:109], v[142:145], v[210:213], v[106:109]
	v_mfma_f32_16x16x32_bf16 v[94:97], v[134:137], v[218:221], v[94:97]
	v_mfma_f32_16x16x32_bf16 v[90:93], v[142:145], v[218:221], v[90:93]
	v_mfma_f32_16x16x32_bf16 v[78:81], v[134:137], v[226:229], v[78:81]
	v_mfma_f32_16x16x32_bf16 v[74:77], v[142:145], v[226:229], v[74:77]
	s_setprio 0
	s_setprio 1
	v_mfma_f32_16x16x32_bf16 v[122:125], v[146:149], v[184:187], 0
	v_mfma_f32_16x16x32_bf16 v[118:121], v[154:157], v[184:187], 0
	v_mfma_f32_16x16x32_bf16 v[102:105], v[146:149], v[206:209], 0
	v_mfma_f32_16x16x32_bf16 v[98:101], v[154:157], v[206:209], 0
	v_mfma_f32_16x16x32_bf16 v[86:89], v[146:149], v[214:217], 0
	v_mfma_f32_16x16x32_bf16 v[82:85], v[154:157], v[214:217], 0
	v_mfma_f32_16x16x32_bf16 v[70:73], v[146:149], v[222:225], 0
	v_mfma_f32_16x16x32_bf16 v[66:69], v[154:157], v[222:225], 0
	v_mfma_f32_16x16x32_bf16 v[122:125], v[150:153], v[188:191], v[122:125]
	v_mfma_f32_16x16x32_bf16 v[118:121], v[158:161], v[188:191], v[118:121]
	v_mfma_f32_16x16x32_bf16 v[102:105], v[150:153], v[210:213], v[102:105]
	v_mfma_f32_16x16x32_bf16 v[98:101], v[158:161], v[210:213], v[98:101]
	v_mfma_f32_16x16x32_bf16 v[86:89], v[150:153], v[218:221], v[86:89]
	v_mfma_f32_16x16x32_bf16 v[82:85], v[158:161], v[218:221], v[82:85]
	v_mfma_f32_16x16x32_bf16 v[70:73], v[150:153], v[226:229], v[70:73]
	v_mfma_f32_16x16x32_bf16 v[66:69], v[158:161], v[226:229], v[66:69]
	s_setprio 0
	s_barrier
	s_add_i32 s0, s89, s79
	s_mov_b32 m0, s0
	ds_read_b128 v[184:187], v199 offset:16384
	ds_read_b128 v[188:191], v199 offset:17408
	ds_read_b128 v[206:209], v199 offset:18432
	ds_read_b128 v[210:213], v199 offset:19456
	ds_read_b128 v[214:217], v199 offset:20480
	ds_read_b128 v[218:221], v199 offset:21504
	ds_read_b128 v[222:225], v199 offset:22528
	ds_read_b128 v[226:229], v199 offset:23552
	global_load_lds_dwordx4 v164, s[8:9]
	s_add_i32 m0, s0, 0x2000
	s_add_u32 s62, s8, 0x40000
	s_addc_u32 s63, s9, 0
	s_add_i32 s0, s90, s79
	global_load_lds_dwordx4 v168, s[8:9]
	s_mov_b32 m0, s0
	s_nop 0
	global_load_lds_dwordx4 v164, s[62:63]
	s_add_i32 m0, s0, 0x2000
	s_nop 0
	global_load_lds_dwordx4 v168, s[62:63]
	s_mov_b32 m0, s31
	s_nop 0
	global_load_lds_dwordx4 v162, s[10:11]
	s_mov_b32 m0, s80
	s_nop 0
	global_load_lds_dwordx4 v166, s[10:11]
	s_waitcnt vmcnt(8)
	s_waitcnt lgkmcnt(0)
	s_barrier
	s_setprio 1
	s_waitcnt lgkmcnt(0)
	v_mfma_f32_16x16x32_bf16 v[62:65], v[114:117], v[184:187], 0
	v_mfma_f32_16x16x32_bf16 v[58:61], v[138:141], v[184:187], 0
	v_mfma_f32_16x16x32_bf16 v[46:49], v[114:117], v[206:209], 0
	v_mfma_f32_16x16x32_bf16 v[42:45], v[138:141], v[206:209], 0
	v_mfma_f32_16x16x32_bf16 v[30:33], v[114:117], v[214:217], 0
	v_mfma_f32_16x16x32_bf16 v[26:29], v[138:141], v[214:217], 0
	v_mfma_f32_16x16x32_bf16 v[14:17], v[114:117], v[222:225], 0
	v_mfma_f32_16x16x32_bf16 v[10:13], v[138:141], v[222:225], 0
	v_mfma_f32_16x16x32_bf16 v[62:65], v[134:137], v[188:191], v[62:65]
	v_mfma_f32_16x16x32_bf16 v[58:61], v[142:145], v[188:191], v[58:61]
	v_mfma_f32_16x16x32_bf16 v[46:49], v[134:137], v[210:213], v[46:49]
	v_mfma_f32_16x16x32_bf16 v[42:45], v[142:145], v[210:213], v[42:45]
	v_mfma_f32_16x16x32_bf16 v[30:33], v[134:137], v[218:221], v[30:33]
	v_mfma_f32_16x16x32_bf16 v[26:29], v[142:145], v[218:221], v[26:29]
	v_mfma_f32_16x16x32_bf16 v[14:17], v[134:137], v[226:229], v[14:17]
	v_mfma_f32_16x16x32_bf16 v[10:13], v[142:145], v[226:229], v[10:13]
	s_setprio 0
	s_setprio 1
	v_mfma_f32_16x16x32_bf16 v[54:57], v[146:149], v[184:187], 0
	v_mfma_f32_16x16x32_bf16 v[50:53], v[154:157], v[184:187], 0
	v_mfma_f32_16x16x32_bf16 v[38:41], v[146:149], v[206:209], 0
	v_mfma_f32_16x16x32_bf16 v[34:37], v[154:157], v[206:209], 0
	v_mfma_f32_16x16x32_bf16 v[22:25], v[146:149], v[214:217], 0
	v_mfma_f32_16x16x32_bf16 v[18:21], v[154:157], v[214:217], 0
	v_mfma_f32_16x16x32_bf16 v[6:9], v[146:149], v[222:225], 0
	v_mfma_f32_16x16x32_bf16 v[2:5], v[154:157], v[222:225], 0
	v_mfma_f32_16x16x32_bf16 v[54:57], v[150:153], v[188:191], v[54:57]
	v_mfma_f32_16x16x32_bf16 v[50:53], v[158:161], v[188:191], v[50:53]
	v_mfma_f32_16x16x32_bf16 v[38:41], v[150:153], v[210:213], v[38:41]
	v_mfma_f32_16x16x32_bf16 v[34:37], v[158:161], v[210:213], v[34:37]
	v_mfma_f32_16x16x32_bf16 v[22:25], v[150:153], v[218:221], v[22:25]
	v_mfma_f32_16x16x32_bf16 v[18:21], v[158:161], v[218:221], v[18:21]
	v_mfma_f32_16x16x32_bf16 v[6:9], v[150:153], v[226:229], v[6:9]
	v_mfma_f32_16x16x32_bf16 v[2:5], v[158:161], v[226:229], v[2:5]
	s_setprio 0
	s_barrier
	s_add_i32 s0, 0, 0x18000
	s_add_i32 s27, 0, 0x1c000
	v_add_u32_e32 v142, s0, v173
	v_add_u32_e32 v158, s27, v173
	ds_read_b128 v[114:117], v142
	ds_read_b128 v[134:137], v142 offset:1024
	ds_read_b128 v[138:141], v142 offset:2048
	ds_read_b128 v[142:145], v142 offset:3072
	ds_read_b128 v[146:149], v158
	ds_read_b128 v[150:153], v158 offset:1024
	ds_read_b128 v[154:157], v158 offset:2048
	ds_read_b128 v[158:161], v158 offset:3072
	s_add_u32 s10, s10, 0x40000
	s_addc_u32 s11, s11, 0
	s_mov_b32 m0, s81
	ds_read_b128 v[184:187], v199 offset:32768
	ds_read_b128 v[188:191], v199 offset:33792
	ds_read_b128 v[206:209], v199 offset:34816
	ds_read_b128 v[210:213], v199 offset:35840
	ds_read_b128 v[214:217], v199 offset:36864
	ds_read_b128 v[218:221], v199 offset:37888
	ds_read_b128 v[222:225], v199 offset:38912
	ds_read_b128 v[226:229], v199 offset:39936
	global_load_lds_dwordx4 v162, s[10:11]
	s_mov_b32 m0, s82
	s_nop 0
	global_load_lds_dwordx4 v166, s[10:11]
	s_waitcnt vmcnt(8)
	s_waitcnt lgkmcnt(0)
	s_barrier
	s_setprio 1
	s_waitcnt lgkmcnt(0)
	v_mfma_f32_16x16x32_bf16 v[130:133], v[114:117], v[184:187], v[130:133]
	v_mfma_f32_16x16x32_bf16 v[126:129], v[138:141], v[184:187], v[126:129]
	v_mfma_f32_16x16x32_bf16 v[110:113], v[114:117], v[206:209], v[110:113]
	v_mfma_f32_16x16x32_bf16 v[106:109], v[138:141], v[206:209], v[106:109]
	v_mfma_f32_16x16x32_bf16 v[94:97], v[114:117], v[214:217], v[94:97]
	v_mfma_f32_16x16x32_bf16 v[90:93], v[138:141], v[214:217], v[90:93]
	v_mfma_f32_16x16x32_bf16 v[78:81], v[114:117], v[222:225], v[78:81]
	v_mfma_f32_16x16x32_bf16 v[74:77], v[138:141], v[222:225], v[74:77]
	v_mfma_f32_16x16x32_bf16 v[130:133], v[134:137], v[188:191], v[130:133]
	v_mfma_f32_16x16x32_bf16 v[126:129], v[142:145], v[188:191], v[126:129]
	v_mfma_f32_16x16x32_bf16 v[110:113], v[134:137], v[210:213], v[110:113]
	v_mfma_f32_16x16x32_bf16 v[106:109], v[142:145], v[210:213], v[106:109]
	v_mfma_f32_16x16x32_bf16 v[94:97], v[134:137], v[218:221], v[94:97]
	v_mfma_f32_16x16x32_bf16 v[90:93], v[142:145], v[218:221], v[90:93]
	v_mfma_f32_16x16x32_bf16 v[78:81], v[134:137], v[226:229], v[78:81]
	v_mfma_f32_16x16x32_bf16 v[74:77], v[142:145], v[226:229], v[74:77]
	s_setprio 0
	s_setprio 1
	v_mfma_f32_16x16x32_bf16 v[122:125], v[146:149], v[184:187], v[122:125]
	v_mfma_f32_16x16x32_bf16 v[118:121], v[154:157], v[184:187], v[118:121]
	v_mfma_f32_16x16x32_bf16 v[102:105], v[146:149], v[206:209], v[102:105]
	v_mfma_f32_16x16x32_bf16 v[98:101], v[154:157], v[206:209], v[98:101]
	v_mfma_f32_16x16x32_bf16 v[86:89], v[146:149], v[214:217], v[86:89]
	v_mfma_f32_16x16x32_bf16 v[82:85], v[154:157], v[214:217], v[82:85]
	v_mfma_f32_16x16x32_bf16 v[70:73], v[146:149], v[222:225], v[70:73]
	v_mfma_f32_16x16x32_bf16 v[66:69], v[154:157], v[222:225], v[66:69]
	v_mfma_f32_16x16x32_bf16 v[122:125], v[150:153], v[188:191], v[122:125]
	v_mfma_f32_16x16x32_bf16 v[118:121], v[158:161], v[188:191], v[118:121]
	v_mfma_f32_16x16x32_bf16 v[102:105], v[150:153], v[210:213], v[102:105]
	v_mfma_f32_16x16x32_bf16 v[98:101], v[158:161], v[210:213], v[98:101]
	v_mfma_f32_16x16x32_bf16 v[86:89], v[150:153], v[218:221], v[86:89]
	v_mfma_f32_16x16x32_bf16 v[82:85], v[158:161], v[218:221], v[82:85]
	v_mfma_f32_16x16x32_bf16 v[70:73], v[150:153], v[226:229], v[70:73]
	v_mfma_f32_16x16x32_bf16 v[66:69], v[158:161], v[226:229], v[66:69]
	s_setprio 0
	s_barrier
	s_add_i32 s0, s0, s79
	s_mov_b32 m0, s0
	ds_read_b128 v[184:187], v199 offset:49152
	ds_read_b128 v[188:191], v199 offset:50176
	ds_read_b128 v[206:209], v199 offset:51200
	ds_read_b128 v[210:213], v199 offset:52224
	ds_read_b128 v[214:217], v199 offset:53248
	ds_read_b128 v[218:221], v199 offset:54272
	ds_read_b128 v[222:225], v199 offset:55296
	ds_read_b128 v[226:229], v199 offset:56320
	s_add_u32 s98, s8, 0x80
	s_addc_u32 s99, s9, 0
	global_load_lds_dwordx4 v164, s[98:99]
	s_add_i32 m0, s0, 0x2000
	s_add_u32 s8, s8, 0x40080
	s_addc_u32 s9, s9, 0
	s_add_i32 s0, s27, s79
	global_load_lds_dwordx4 v168, s[98:99]
	s_mov_b32 m0, s0
	s_nop 0
	global_load_lds_dwordx4 v164, s[8:9]
	s_add_i32 m0, s0, 0x2000
	s_nop 0
	global_load_lds_dwordx4 v168, s[8:9]
	s_add_u32 s98, s10, 0xfffc0080
	s_addc_u32 s99, s11, -1
	s_mov_b32 m0, s84
	s_nop 0
	global_load_lds_dwordx4 v162, s[98:99]
	s_mov_b32 m0, s85
	s_nop 0
	global_load_lds_dwordx4 v166, s[98:99]
	s_waitcnt vmcnt(8)
	s_waitcnt lgkmcnt(0)
	s_barrier
	s_setprio 1
	s_waitcnt lgkmcnt(0)
	v_mfma_f32_16x16x32_bf16 v[62:65], v[114:117], v[184:187], v[62:65]
	v_mfma_f32_16x16x32_bf16 v[58:61], v[138:141], v[184:187], v[58:61]
	v_mfma_f32_16x16x32_bf16 v[46:49], v[114:117], v[206:209], v[46:49]
	v_mfma_f32_16x16x32_bf16 v[42:45], v[138:141], v[206:209], v[42:45]
	v_mfma_f32_16x16x32_bf16 v[30:33], v[114:117], v[214:217], v[30:33]
	v_mfma_f32_16x16x32_bf16 v[26:29], v[138:141], v[214:217], v[26:29]
	v_mfma_f32_16x16x32_bf16 v[14:17], v[114:117], v[222:225], v[14:17]
	v_mfma_f32_16x16x32_bf16 v[10:13], v[138:141], v[222:225], v[10:13]
	v_mfma_f32_16x16x32_bf16 v[62:65], v[134:137], v[188:191], v[62:65]
	v_mfma_f32_16x16x32_bf16 v[58:61], v[142:145], v[188:191], v[58:61]
	v_mfma_f32_16x16x32_bf16 v[46:49], v[134:137], v[210:213], v[46:49]
	v_mfma_f32_16x16x32_bf16 v[42:45], v[142:145], v[210:213], v[42:45]
	v_mfma_f32_16x16x32_bf16 v[30:33], v[134:137], v[218:221], v[30:33]
	v_mfma_f32_16x16x32_bf16 v[26:29], v[142:145], v[218:221], v[26:29]
	v_mfma_f32_16x16x32_bf16 v[14:17], v[134:137], v[226:229], v[14:17]
	v_mfma_f32_16x16x32_bf16 v[10:13], v[142:145], v[226:229], v[10:13]
	s_setprio 0
	s_setprio 1
	v_mfma_f32_16x16x32_bf16 v[54:57], v[146:149], v[184:187], v[54:57]
	v_mfma_f32_16x16x32_bf16 v[50:53], v[154:157], v[184:187], v[50:53]
	v_mfma_f32_16x16x32_bf16 v[38:41], v[146:149], v[206:209], v[38:41]
	v_mfma_f32_16x16x32_bf16 v[34:37], v[154:157], v[206:209], v[34:37]
	v_mfma_f32_16x16x32_bf16 v[22:25], v[146:149], v[214:217], v[22:25]
	v_mfma_f32_16x16x32_bf16 v[18:21], v[154:157], v[214:217], v[18:21]
	v_mfma_f32_16x16x32_bf16 v[6:9], v[146:149], v[222:225], v[6:9]
	v_mfma_f32_16x16x32_bf16 v[2:5], v[154:157], v[222:225], v[2:5]
	v_mfma_f32_16x16x32_bf16 v[54:57], v[150:153], v[188:191], v[54:57]
	v_mfma_f32_16x16x32_bf16 v[50:53], v[158:161], v[188:191], v[50:53]
	v_mfma_f32_16x16x32_bf16 v[38:41], v[150:153], v[210:213], v[38:41]
	v_mfma_f32_16x16x32_bf16 v[34:37], v[158:161], v[210:213], v[34:37]
	v_mfma_f32_16x16x32_bf16 v[22:25], v[150:153], v[218:221], v[22:25]
	v_mfma_f32_16x16x32_bf16 v[18:21], v[158:161], v[218:221], v[18:21]
	v_mfma_f32_16x16x32_bf16 v[6:9], v[150:153], v[226:229], v[6:9]
	v_mfma_f32_16x16x32_bf16 v[2:5], v[158:161], v[226:229], v[2:5]
	s_setprio 0
	s_barrier
	s_add_i32 s26, s26, 2
	s_add_u32 s6, s6, 0x100
	s_addc_u32 s7, s7, 0
	s_add_u32 s24, s24, 0x100
	s_addc_u32 s25, s25, 0
	s_cmp_gt_u32 s26, 13
	s_cbranch_scc1 .Lpeel_x1

.Lpeel_x1:
	s_and_b64 vcc, exec, s[46:47]
	s_cbranch_vccz .LBB0_371

.LBB0_902:
	s_mov_b64 s[28:29], s[10:11]
	s_mov_b32 s10, s37
	s_mov_b32 s0, s37
	s_add_i32 s37, s47, s1
	s_mov_b64 s[30:31], s[8:9]
	s_and_b64 s[8:9], s[26:27], exec
	s_cselect_b32 s8, s37, s10
	s_cselect_b32 s10, s46, s46
	s_ashr_i32 s11, s10, 31
	s_lshl_b64 s[10:11], s[10:11], 19
	s_add_u32 s10, s2, s10
	s_addc_u32 s11, s3, s11
	s_and_b64 s[34:35], s[26:27], exec
	s_cselect_b32 s1, s11, s29
	s_cselect_b32 s50, s10, s28
	s_ashr_i32 s9, s8, 31
	s_lshl_b64 s[8:9], s[8:9], 19
	s_add_u32 s8, s4, s8
	s_addc_u32 s9, s5, s9
	s_and_b64 s[34:35], s[26:27], exec
	s_cselect_b32 s51, s9, s31
	s_cselect_b32 s52, s8, s30
	s_add_u32 s28, s28, 0x40080
	s_addc_u32 s29, s29, 0
	s_add_u32 s53, s30, 0x100
	s_addc_u32 s54, s31, 0
	s_mov_b32 s55, -2
	s_waitcnt lgkmcnt(0)
	ds_read_b128 v[130:133], v209
	ds_read_b128 v[134:137], v209 offset:1024
	ds_read_b128 v[138:141], v209 offset:2048
	ds_read_b128 v[142:145], v209 offset:3072
	ds_read_b128 v[146:149], v210
	ds_read_b128 v[150:153], v210 offset:1024
	ds_read_b128 v[154:157], v210 offset:2048
	ds_read_b128 v[158:161], v210 offset:3072
	s_add_u32 s30, s28, 0xfffc0080
	s_addc_u32 s31, s29, -1
	s_cmp_eq_u32 s55, 12
	s_cselect_b32 s35, s1, s31
	s_cselect_b32 s34, s50, s30
	s_cselect_b32 s31, s51, s54
	s_cselect_b32 s30, s52, s53
	v_lshl_add_u64 v[216:217], s[28:29], 0, v[190:191]
	s_add_i32 m0, s39, 0xc000
	ds_read_b128 v[162:165], v211
	ds_read_b128 v[166:169], v211 offset:1024
	ds_read_b128 v[170:173], v211 offset:2048
	ds_read_b128 v[174:177], v211 offset:3072
	ds_read_b128 v[194:197], v211 offset:4096
	ds_read_b128 v[198:201], v211 offset:5120
	ds_read_b128 v[202:205], v211 offset:6144
	ds_read_b128 v[212:215], v211 offset:7168
	global_load_lds_dwordx4 v[216:217], off
	v_lshl_add_u64 v[216:217], s[28:29], 0, v[192:193]
	s_add_i32 m0, s39, 0xe000
	s_nop 0
	global_load_lds_dwordx4 v[216:217], off
	s_waitcnt vmcnt(8)
	s_waitcnt lgkmcnt(0)
	s_barrier
	s_setprio 1
	s_waitcnt lgkmcnt(0)
	v_mfma_f32_16x16x32_bf16 v[126:129], v[130:133], v[162:165], 0
	v_mfma_f32_16x16x32_bf16 v[122:125], v[138:141], v[162:165], 0
	v_mfma_f32_16x16x32_bf16 v[110:113], v[130:133], v[170:173], 0
	v_mfma_f32_16x16x32_bf16 v[106:109], v[138:141], v[170:173], 0
	v_mfma_f32_16x16x32_bf16 v[94:97], v[130:133], v[194:197], 0
	v_mfma_f32_16x16x32_bf16 v[90:93], v[138:141], v[194:197], 0
	v_mfma_f32_16x16x32_bf16 v[78:81], v[130:133], v[202:205], 0
	v_mfma_f32_16x16x32_bf16 v[74:77], v[138:141], v[202:205], 0
	v_mfma_f32_16x16x32_bf16 v[126:129], v[134:137], v[166:169], v[126:129]
	v_mfma_f32_16x16x32_bf16 v[122:125], v[142:145], v[166:169], v[122:125]
	v_mfma_f32_16x16x32_bf16 v[110:113], v[134:137], v[174:177], v[110:113]
	v_mfma_f32_16x16x32_bf16 v[106:109], v[142:145], v[174:177], v[106:109]
	v_mfma_f32_16x16x32_bf16 v[94:97], v[134:137], v[198:201], v[94:97]
	v_mfma_f32_16x16x32_bf16 v[90:93], v[142:145], v[198:201], v[90:93]
	v_mfma_f32_16x16x32_bf16 v[78:81], v[134:137], v[212:215], v[78:81]
	v_mfma_f32_16x16x32_bf16 v[74:77], v[142:145], v[212:215], v[74:77]
	s_setprio 0
	s_setprio 1
	v_mfma_f32_16x16x32_bf16 v[118:121], v[146:149], v[162:165], 0
	v_mfma_f32_16x16x32_bf16 v[114:117], v[154:157], v[162:165], 0
	v_mfma_f32_16x16x32_bf16 v[102:105], v[146:149], v[170:173], 0
	v_mfma_f32_16x16x32_bf16 v[98:101], v[154:157], v[170:173], 0
	v_mfma_f32_16x16x32_bf16 v[86:89], v[146:149], v[194:197], 0
	v_mfma_f32_16x16x32_bf16 v[82:85], v[154:157], v[194:197], 0
	v_mfma_f32_16x16x32_bf16 v[70:73], v[146:149], v[202:205], 0
	v_mfma_f32_16x16x32_bf16 v[66:69], v[154:157], v[202:205], 0
	v_mfma_f32_16x16x32_bf16 v[118:121], v[150:153], v[166:169], v[118:121]
	v_mfma_f32_16x16x32_bf16 v[114:117], v[158:161], v[166:169], v[114:117]
	v_mfma_f32_16x16x32_bf16 v[102:105], v[150:153], v[174:177], v[102:105]
	v_mfma_f32_16x16x32_bf16 v[98:101], v[158:161], v[174:177], v[98:101]
	v_mfma_f32_16x16x32_bf16 v[86:89], v[150:153], v[198:201], v[86:89]
	v_mfma_f32_16x16x32_bf16 v[82:85], v[158:161], v[198:201], v[82:85]
	v_mfma_f32_16x16x32_bf16 v[70:73], v[150:153], v[212:215], v[70:73]
	v_mfma_f32_16x16x32_bf16 v[66:69], v[158:161], v[212:215], v[66:69]
	s_setprio 0
	s_barrier
	s_add_i32 s56, s48, s38
	v_lshl_add_u64 v[216:217], s[30:31], 0, v[184:185]
	s_mov_b32 m0, s56
	ds_read_b128 v[162:165], v211 offset:16384
	ds_read_b128 v[166:169], v211 offset:17408
	ds_read_b128 v[170:173], v211 offset:18432
	ds_read_b128 v[174:177], v211 offset:19456
	ds_read_b128 v[194:197], v211 offset:20480
	ds_read_b128 v[198:201], v211 offset:21504
	ds_read_b128 v[202:205], v211 offset:22528
	ds_read_b128 v[212:215], v211 offset:23552
	global_load_lds_dwordx4 v[216:217], off
	s_add_i32 m0, s56, 0x2000
	s_add_u32 s56, s30, 0x40000
	v_lshl_add_u64 v[218:219], s[30:31], 0, v[188:189]
	s_addc_u32 s57, s31, 0
	s_add_i32 s58, s49, s38
	global_load_lds_dwordx4 v[218:219], off
	v_lshl_add_u64 v[220:221], s[56:57], 0, v[184:185]
	s_mov_b32 m0, s58
	v_lshl_add_u64 v[222:223], s[34:35], 0, v[186:187]
	global_load_lds_dwordx4 v[220:221], off
	v_lshl_add_u64 v[220:221], s[56:57], 0, v[188:189]
	s_add_i32 m0, s58, 0x2000
	s_nop 0
	global_load_lds_dwordx4 v[220:221], off
	v_lshl_add_u64 v[220:221], s[34:35], 0, v[182:183]
	s_mov_b32 m0, s39
	s_nop 0
	global_load_lds_dwordx4 v[220:221], off
	s_mov_b32 m0, s40
	s_nop 0
	global_load_lds_dwordx4 v[222:223], off
	s_waitcnt vmcnt(8)
	s_waitcnt lgkmcnt(0)
	s_barrier
	s_setprio 1
	s_waitcnt lgkmcnt(0)
	v_mfma_f32_16x16x32_bf16 v[62:65], v[130:133], v[162:165], 0
	v_mfma_f32_16x16x32_bf16 v[58:61], v[138:141], v[162:165], 0
	v_mfma_f32_16x16x32_bf16 v[46:49], v[130:133], v[170:173], 0
	v_mfma_f32_16x16x32_bf16 v[42:45], v[138:141], v[170:173], 0
	v_mfma_f32_16x16x32_bf16 v[30:33], v[130:133], v[194:197], 0
	v_mfma_f32_16x16x32_bf16 v[26:29], v[138:141], v[194:197], 0
	v_mfma_f32_16x16x32_bf16 v[14:17], v[130:133], v[202:205], 0
	v_mfma_f32_16x16x32_bf16 v[10:13], v[138:141], v[202:205], 0
	v_mfma_f32_16x16x32_bf16 v[62:65], v[134:137], v[166:169], v[62:65]
	v_mfma_f32_16x16x32_bf16 v[58:61], v[142:145], v[166:169], v[58:61]
	v_mfma_f32_16x16x32_bf16 v[46:49], v[134:137], v[174:177], v[46:49]
	v_mfma_f32_16x16x32_bf16 v[42:45], v[142:145], v[174:177], v[42:45]
	v_mfma_f32_16x16x32_bf16 v[30:33], v[134:137], v[198:201], v[30:33]
	v_mfma_f32_16x16x32_bf16 v[26:29], v[142:145], v[198:201], v[26:29]
	v_mfma_f32_16x16x32_bf16 v[14:17], v[134:137], v[212:215], v[14:17]
	v_mfma_f32_16x16x32_bf16 v[10:13], v[142:145], v[212:215], v[10:13]
	s_setprio 0
	s_setprio 1
	v_mfma_f32_16x16x32_bf16 v[54:57], v[146:149], v[162:165], 0
	v_mfma_f32_16x16x32_bf16 v[50:53], v[154:157], v[162:165], 0
	v_mfma_f32_16x16x32_bf16 v[38:41], v[146:149], v[170:173], 0
	v_mfma_f32_16x16x32_bf16 v[34:37], v[154:157], v[170:173], 0
	v_mfma_f32_16x16x32_bf16 v[22:25], v[146:149], v[194:197], 0
	v_mfma_f32_16x16x32_bf16 v[18:21], v[154:157], v[194:197], 0
	v_mfma_f32_16x16x32_bf16 v[6:9], v[146:149], v[202:205], 0
	v_mfma_f32_16x16x32_bf16 v[2:5], v[154:157], v[202:205], 0
	v_mfma_f32_16x16x32_bf16 v[54:57], v[150:153], v[166:169], v[54:57]
	v_mfma_f32_16x16x32_bf16 v[50:53], v[158:161], v[166:169], v[50:53]
	v_mfma_f32_16x16x32_bf16 v[38:41], v[150:153], v[174:177], v[38:41]
	v_mfma_f32_16x16x32_bf16 v[34:37], v[158:161], v[174:177], v[34:37]
	v_mfma_f32_16x16x32_bf16 v[22:25], v[150:153], v[198:201], v[22:25]
	v_mfma_f32_16x16x32_bf16 v[18:21], v[158:161], v[198:201], v[18:21]
	v_mfma_f32_16x16x32_bf16 v[6:9], v[150:153], v[212:215], v[6:9]
	v_mfma_f32_16x16x32_bf16 v[2:5], v[158:161], v[212:215], v[2:5]
	s_setprio 0
	s_barrier
	s_add_i32 s56, 0, 0x18000
	s_add_i32 s57, 0, 0x1c000
	v_add_u32_e32 v142, s56, v207
	v_add_u32_e32 v158, s57, v207
	ds_read_b128 v[130:133], v142
	ds_read_b128 v[134:137], v142 offset:1024
	ds_read_b128 v[138:141], v142 offset:2048
	ds_read_b128 v[142:145], v142 offset:3072
	ds_read_b128 v[146:149], v158
	ds_read_b128 v[150:153], v158 offset:1024
	ds_read_b128 v[154:157], v158 offset:2048
	ds_read_b128 v[158:161], v158 offset:3072
	s_add_u32 s34, s34, 0x40000
	s_addc_u32 s35, s35, 0
	s_mov_b32 m0, s41
	v_lshl_add_u64 v[224:225], s[34:35], 0, v[182:183]
	ds_read_b128 v[162:165], v211 offset:32768
	ds_read_b128 v[166:169], v211 offset:33792
	ds_read_b128 v[170:173], v211 offset:34816
	ds_read_b128 v[174:177], v211 offset:35840
	ds_read_b128 v[194:197], v211 offset:36864
	ds_read_b128 v[198:201], v211 offset:37888
	ds_read_b128 v[202:205], v211 offset:38912
	ds_read_b128 v[212:215], v211 offset:39936
	global_load_lds_dwordx4 v[224:225], off
	v_lshl_add_u64 v[224:225], s[34:35], 0, v[186:187]
	s_mov_b32 m0, s42
	s_nop 0
	global_load_lds_dwordx4 v[224:225], off
	s_waitcnt vmcnt(8)
	s_waitcnt lgkmcnt(0)
	s_barrier
	s_setprio 1
	s_waitcnt lgkmcnt(0)
	v_mfma_f32_16x16x32_bf16 v[126:129], v[130:133], v[162:165], v[126:129]
	v_mfma_f32_16x16x32_bf16 v[122:125], v[138:141], v[162:165], v[122:125]
	v_mfma_f32_16x16x32_bf16 v[110:113], v[130:133], v[170:173], v[110:113]
	v_mfma_f32_16x16x32_bf16 v[106:109], v[138:141], v[170:173], v[106:109]
	v_mfma_f32_16x16x32_bf16 v[94:97], v[130:133], v[194:197], v[94:97]
	v_mfma_f32_16x16x32_bf16 v[90:93], v[138:141], v[194:197], v[90:93]
	v_mfma_f32_16x16x32_bf16 v[78:81], v[130:133], v[202:205], v[78:81]
	v_mfma_f32_16x16x32_bf16 v[74:77], v[138:141], v[202:205], v[74:77]
	v_mfma_f32_16x16x32_bf16 v[126:129], v[134:137], v[166:169], v[126:129]
	v_mfma_f32_16x16x32_bf16 v[122:125], v[142:145], v[166:169], v[122:125]
	v_mfma_f32_16x16x32_bf16 v[110:113], v[134:137], v[174:177], v[110:113]
	v_mfma_f32_16x16x32_bf16 v[106:109], v[142:145], v[174:177], v[106:109]
	v_mfma_f32_16x16x32_bf16 v[94:97], v[134:137], v[198:201], v[94:97]
	v_mfma_f32_16x16x32_bf16 v[90:93], v[142:145], v[198:201], v[90:93]
	v_mfma_f32_16x16x32_bf16 v[78:81], v[134:137], v[212:215], v[78:81]
	v_mfma_f32_16x16x32_bf16 v[74:77], v[142:145], v[212:215], v[74:77]
	s_setprio 0
	s_setprio 1
	v_mfma_f32_16x16x32_bf16 v[118:121], v[146:149], v[162:165], v[118:121]
	v_mfma_f32_16x16x32_bf16 v[114:117], v[154:157], v[162:165], v[114:117]
	v_mfma_f32_16x16x32_bf16 v[102:105], v[146:149], v[170:173], v[102:105]
	v_mfma_f32_16x16x32_bf16 v[98:101], v[154:157], v[170:173], v[98:101]
	v_mfma_f32_16x16x32_bf16 v[86:89], v[146:149], v[194:197], v[86:89]
	v_mfma_f32_16x16x32_bf16 v[82:85], v[154:157], v[194:197], v[82:85]
	v_mfma_f32_16x16x32_bf16 v[70:73], v[146:149], v[202:205], v[70:73]
	v_mfma_f32_16x16x32_bf16 v[66:69], v[154:157], v[202:205], v[66:69]
	v_mfma_f32_16x16x32_bf16 v[118:121], v[150:153], v[166:169], v[118:121]
	v_mfma_f32_16x16x32_bf16 v[114:117], v[158:161], v[166:169], v[114:117]
	v_mfma_f32_16x16x32_bf16 v[102:105], v[150:153], v[174:177], v[102:105]
	v_mfma_f32_16x16x32_bf16 v[98:101], v[158:161], v[174:177], v[98:101]
	v_mfma_f32_16x16x32_bf16 v[86:89], v[150:153], v[198:201], v[86:89]
	v_mfma_f32_16x16x32_bf16 v[82:85], v[158:161], v[198:201], v[82:85]
	v_mfma_f32_16x16x32_bf16 v[70:73], v[150:153], v[212:215], v[70:73]
	v_mfma_f32_16x16x32_bf16 v[66:69], v[158:161], v[212:215], v[66:69]
	s_setprio 0
	s_barrier
	s_add_i32 s34, s56, s38
	v_lshl_add_u64 v[216:217], v[216:217], 0, s[22:23]
	s_mov_b32 m0, s34
	ds_read_b128 v[162:165], v211 offset:49152
	ds_read_b128 v[166:169], v211 offset:50176
	ds_read_b128 v[170:173], v211 offset:51200
	ds_read_b128 v[174:177], v211 offset:52224
	ds_read_b128 v[194:197], v211 offset:53248
	ds_read_b128 v[198:201], v211 offset:54272
	ds_read_b128 v[202:205], v211 offset:55296
	ds_read_b128 v[212:215], v211 offset:56320
	global_load_lds_dwordx4 v[216:217], off
	s_add_i32 m0, s34, 0x2000
	s_add_u32 s30, s30, 0x40080
	v_lshl_add_u64 v[216:217], v[218:219], 0, s[22:23]
	s_addc_u32 s31, s31, 0
	s_add_i32 s34, s57, s38
	global_load_lds_dwordx4 v[216:217], off
	v_lshl_add_u64 v[216:217], s[30:31], 0, v[184:185]
	s_mov_b32 m0, s34
	s_nop 0
	global_load_lds_dwordx4 v[216:217], off
	v_lshl_add_u64 v[216:217], s[30:31], 0, v[188:189]
	s_add_i32 m0, s34, 0x2000
	s_nop 0
	global_load_lds_dwordx4 v[216:217], off
	v_lshl_add_u64 v[216:217], v[220:221], 0, s[22:23]
	s_mov_b32 m0, s44
	s_nop 0
	global_load_lds_dwordx4 v[216:217], off
	v_lshl_add_u64 v[216:217], v[222:223], 0, s[22:23]
	s_mov_b32 m0, s45
	s_nop 0
	global_load_lds_dwordx4 v[216:217], off
	s_waitcnt vmcnt(8)
	s_waitcnt lgkmcnt(0)
	s_barrier
	s_setprio 1
	s_waitcnt lgkmcnt(0)
	v_mfma_f32_16x16x32_bf16 v[62:65], v[130:133], v[162:165], v[62:65]
	v_mfma_f32_16x16x32_bf16 v[58:61], v[138:141], v[162:165], v[58:61]
	v_mfma_f32_16x16x32_bf16 v[46:49], v[130:133], v[170:173], v[46:49]
	v_mfma_f32_16x16x32_bf16 v[42:45], v[138:141], v[170:173], v[42:45]
	v_mfma_f32_16x16x32_bf16 v[30:33], v[130:133], v[194:197], v[30:33]
	v_mfma_f32_16x16x32_bf16 v[26:29], v[138:141], v[194:197], v[26:29]
	v_mfma_f32_16x16x32_bf16 v[14:17], v[130:133], v[202:205], v[14:17]
	v_mfma_f32_16x16x32_bf16 v[10:13], v[138:141], v[202:205], v[10:13]
	v_mfma_f32_16x16x32_bf16 v[62:65], v[134:137], v[166:169], v[62:65]
	v_mfma_f32_16x16x32_bf16 v[58:61], v[142:145], v[166:169], v[58:61]
	v_mfma_f32_16x16x32_bf16 v[46:49], v[134:137], v[174:177], v[46:49]
	v_mfma_f32_16x16x32_bf16 v[42:45], v[142:145], v[174:177], v[42:45]
	v_mfma_f32_16x16x32_bf16 v[30:33], v[134:137], v[198:201], v[30:33]
	v_mfma_f32_16x16x32_bf16 v[26:29], v[142:145], v[198:201], v[26:29]
	v_mfma_f32_16x16x32_bf16 v[14:17], v[134:137], v[212:215], v[14:17]
	v_mfma_f32_16x16x32_bf16 v[10:13], v[142:145], v[212:215], v[10:13]
	s_setprio 0
	s_setprio 1
	v_mfma_f32_16x16x32_bf16 v[54:57], v[146:149], v[162:165], v[54:57]
	v_mfma_f32_16x16x32_bf16 v[50:53], v[154:157], v[162:165], v[50:53]
	v_mfma_f32_16x16x32_bf16 v[38:41], v[146:149], v[170:173], v[38:41]
	v_mfma_f32_16x16x32_bf16 v[34:37], v[154:157], v[170:173], v[34:37]
	v_mfma_f32_16x16x32_bf16 v[22:25], v[146:149], v[194:197], v[22:25]
	v_mfma_f32_16x16x32_bf16 v[18:21], v[154:157], v[194:197], v[18:21]
	v_mfma_f32_16x16x32_bf16 v[6:9], v[146:149], v[202:205], v[6:9]
	v_mfma_f32_16x16x32_bf16 v[2:5], v[154:157], v[202:205], v[2:5]
	v_mfma_f32_16x16x32_bf16 v[54:57], v[150:153], v[166:169], v[54:57]
	v_mfma_f32_16x16x32_bf16 v[50:53], v[158:161], v[166:169], v[50:53]
	v_mfma_f32_16x16x32_bf16 v[38:41], v[150:153], v[174:177], v[38:41]
	v_mfma_f32_16x16x32_bf16 v[34:37], v[158:161], v[174:177], v[34:37]
	v_mfma_f32_16x16x32_bf16 v[22:25], v[150:153], v[198:201], v[22:25]
	v_mfma_f32_16x16x32_bf16 v[18:21], v[158:161], v[198:201], v[18:21]
	v_mfma_f32_16x16x32_bf16 v[6:9], v[150:153], v[212:215], v[6:9]
	v_mfma_f32_16x16x32_bf16 v[2:5], v[158:161], v[212:215], v[2:5]
	s_setprio 0
	s_barrier
	s_add_i32 s55, s55, 2
	s_add_u32 s28, s28, 0x100
	s_addc_u32 s29, s29, 0
	s_add_u32 s53, s53, 0x100
	s_addc_u32 s54, s54, 0
	s_cmp_gt_u32 s55, 13
	s_cbranch_scc1 .Lpeel_x3
.LBB0_903:
	ds_read_b128 v[130:133], v209
	ds_read_b128 v[134:137], v209 offset:1024
	ds_read_b128 v[138:141], v209 offset:2048
	ds_read_b128 v[142:145], v209 offset:3072
	ds_read_b128 v[146:149], v210
	ds_read_b128 v[150:153], v210 offset:1024
	ds_read_b128 v[154:157], v210 offset:2048
	ds_read_b128 v[158:161], v210 offset:3072
	s_add_u32 s30, s28, 0xfffc0080
	s_addc_u32 s31, s29, -1
	s_cmp_eq_u32 s55, 12
	s_cselect_b32 s35, s1, s31
	s_cselect_b32 s34, s50, s30
	s_cselect_b32 s31, s51, s54
	s_cselect_b32 s30, s52, s53
	v_lshl_add_u64 v[216:217], s[28:29], 0, v[190:191]
	s_add_i32 m0, s39, 0xc000
	ds_read_b128 v[162:165], v211
	ds_read_b128 v[166:169], v211 offset:1024
	ds_read_b128 v[170:173], v211 offset:2048
	ds_read_b128 v[174:177], v211 offset:3072
	ds_read_b128 v[194:197], v211 offset:4096
	ds_read_b128 v[198:201], v211 offset:5120
	ds_read_b128 v[202:205], v211 offset:6144
	ds_read_b128 v[212:215], v211 offset:7168
	global_load_lds_dwordx4 v[216:217], off
	v_lshl_add_u64 v[216:217], s[28:29], 0, v[192:193]
	s_add_i32 m0, s39, 0xe000
	s_nop 0
	global_load_lds_dwordx4 v[216:217], off
	s_waitcnt vmcnt(8)
	s_waitcnt lgkmcnt(0)
	s_barrier
	s_setprio 1
	s_waitcnt lgkmcnt(0)
	v_mfma_f32_16x16x32_bf16 v[126:129], v[130:133], v[162:165], v[126:129]
	v_mfma_f32_16x16x32_bf16 v[122:125], v[138:141], v[162:165], v[122:125]
	v_mfma_f32_16x16x32_bf16 v[110:113], v[130:133], v[170:173], v[110:113]
	v_mfma_f32_16x16x32_bf16 v[106:109], v[138:141], v[170:173], v[106:109]
	v_mfma_f32_16x16x32_bf16 v[94:97], v[130:133], v[194:197], v[94:97]
	v_mfma_f32_16x16x32_bf16 v[90:93], v[138:141], v[194:197], v[90:93]
	v_mfma_f32_16x16x32_bf16 v[78:81], v[130:133], v[202:205], v[78:81]
	v_mfma_f32_16x16x32_bf16 v[74:77], v[138:141], v[202:205], v[74:77]
	v_mfma_f32_16x16x32_bf16 v[126:129], v[134:137], v[166:169], v[126:129]
	v_mfma_f32_16x16x32_bf16 v[122:125], v[142:145], v[166:169], v[122:125]
	v_mfma_f32_16x16x32_bf16 v[110:113], v[134:137], v[174:177], v[110:113]
	v_mfma_f32_16x16x32_bf16 v[106:109], v[142:145], v[174:177], v[106:109]
	v_mfma_f32_16x16x32_bf16 v[94:97], v[134:137], v[198:201], v[94:97]
	v_mfma_f32_16x16x32_bf16 v[90:93], v[142:145], v[198:201], v[90:93]
	v_mfma_f32_16x16x32_bf16 v[78:81], v[134:137], v[212:215], v[78:81]
	v_mfma_f32_16x16x32_bf16 v[74:77], v[142:145], v[212:215], v[74:77]
	s_setprio 0
	s_setprio 1
	v_mfma_f32_16x16x32_bf16 v[118:121], v[146:149], v[162:165], v[118:121]
	v_mfma_f32_16x16x32_bf16 v[114:117], v[154:157], v[162:165], v[114:117]
	v_mfma_f32_16x16x32_bf16 v[102:105], v[146:149], v[170:173], v[102:105]
	v_mfma_f32_16x16x32_bf16 v[98:101], v[154:157], v[170:173], v[98:101]
	v_mfma_f32_16x16x32_bf16 v[86:89], v[146:149], v[194:197], v[86:89]
	v_mfma_f32_16x16x32_bf16 v[82:85], v[154:157], v[194:197], v[82:85]
	v_mfma_f32_16x16x32_bf16 v[70:73], v[146:149], v[202:205], v[70:73]
	v_mfma_f32_16x16x32_bf16 v[66:69], v[154:157], v[202:205], v[66:69]
	v_mfma_f32_16x16x32_bf16 v[118:121], v[150:153], v[166:169], v[118:121]
	v_mfma_f32_16x16x32_bf16 v[114:117], v[158:161], v[166:169], v[114:117]
	v_mfma_f32_16x16x32_bf16 v[102:105], v[150:153], v[174:177], v[102:105]
	v_mfma_f32_16x16x32_bf16 v[98:101], v[158:161], v[174:177], v[98:101]
	v_mfma_f32_16x16x32_bf16 v[86:89], v[150:153], v[198:201], v[86:89]
	v_mfma_f32_16x16x32_bf16 v[82:85], v[158:161], v[198:201], v[82:85]
	v_mfma_f32_16x16x32_bf16 v[70:73], v[150:153], v[212:215], v[70:73]
	v_mfma_f32_16x16x32_bf16 v[66:69], v[158:161], v[212:215], v[66:69]
	s_setprio 0
	s_barrier
	s_add_i32 s56, s48, s38
	v_lshl_add_u64 v[216:217], s[30:31], 0, v[184:185]
	s_mov_b32 m0, s56
	ds_read_b128 v[162:165], v211 offset:16384
	ds_read_b128 v[166:169], v211 offset:17408
	ds_read_b128 v[170:173], v211 offset:18432
	ds_read_b128 v[174:177], v211 offset:19456
	ds_read_b128 v[194:197], v211 offset:20480
	ds_read_b128 v[198:201], v211 offset:21504
	ds_read_b128 v[202:205], v211 offset:22528
	ds_read_b128 v[212:215], v211 offset:23552
	global_load_lds_dwordx4 v[216:217], off
	s_add_i32 m0, s56, 0x2000
	s_add_u32 s56, s30, 0x40000
	v_lshl_add_u64 v[218:219], s[30:31], 0, v[188:189]
	s_addc_u32 s57, s31, 0
	s_add_i32 s58, s49, s38
	global_load_lds_dwordx4 v[218:219], off
	v_lshl_add_u64 v[220:221], s[56:57], 0, v[184:185]
	s_mov_b32 m0, s58
	v_lshl_add_u64 v[222:223], s[34:35], 0, v[186:187]
	global_load_lds_dwordx4 v[220:221], off
	v_lshl_add_u64 v[220:221], s[56:57], 0, v[188:189]
	s_add_i32 m0, s58, 0x2000
	s_nop 0
	global_load_lds_dwordx4 v[220:221], off
	v_lshl_add_u64 v[220:221], s[34:35], 0, v[182:183]
	s_mov_b32 m0, s39
	s_nop 0
	global_load_lds_dwordx4 v[220:221], off
	s_mov_b32 m0, s40
	s_nop 0
	global_load_lds_dwordx4 v[222:223], off
	s_waitcnt vmcnt(8)
	s_waitcnt lgkmcnt(0)
	s_barrier
	s_setprio 1
	s_waitcnt lgkmcnt(0)
	v_mfma_f32_16x16x32_bf16 v[62:65], v[130:133], v[162:165], v[62:65]
	v_mfma_f32_16x16x32_bf16 v[58:61], v[138:141], v[162:165], v[58:61]
	v_mfma_f32_16x16x32_bf16 v[46:49], v[130:133], v[170:173], v[46:49]
	v_mfma_f32_16x16x32_bf16 v[42:45], v[138:141], v[170:173], v[42:45]
	v_mfma_f32_16x16x32_bf16 v[30:33], v[130:133], v[194:197], v[30:33]
	v_mfma_f32_16x16x32_bf16 v[26:29], v[138:141], v[194:197], v[26:29]
	v_mfma_f32_16x16x32_bf16 v[14:17], v[130:133], v[202:205], v[14:17]
	v_mfma_f32_16x16x32_bf16 v[10:13], v[138:141], v[202:205], v[10:13]
	v_mfma_f32_16x16x32_bf16 v[62:65], v[134:137], v[166:169], v[62:65]
	v_mfma_f32_16x16x32_bf16 v[58:61], v[142:145], v[166:169], v[58:61]
	v_mfma_f32_16x16x32_bf16 v[46:49], v[134:137], v[174:177], v[46:49]
	v_mfma_f32_16x16x32_bf16 v[42:45], v[142:145], v[174:177], v[42:45]
	v_mfma_f32_16x16x32_bf16 v[30:33], v[134:137], v[198:201], v[30:33]
	v_mfma_f32_16x16x32_bf16 v[26:29], v[142:145], v[198:201], v[26:29]
	v_mfma_f32_16x16x32_bf16 v[14:17], v[134:137], v[212:215], v[14:17]
	v_mfma_f32_16x16x32_bf16 v[10:13], v[142:145], v[212:215], v[10:13]
	s_setprio 0
	s_setprio 1
	v_mfma_f32_16x16x32_bf16 v[54:57], v[146:149], v[162:165], v[54:57]
	v_mfma_f32_16x16x32_bf16 v[50:53], v[154:157], v[162:165], v[50:53]
	v_mfma_f32_16x16x32_bf16 v[38:41], v[146:149], v[170:173], v[38:41]
	v_mfma_f32_16x16x32_bf16 v[34:37], v[154:157], v[170:173], v[34:37]
	v_mfma_f32_16x16x32_bf16 v[22:25], v[146:149], v[194:197], v[22:25]
	v_mfma_f32_16x16x32_bf16 v[18:21], v[154:157], v[194:197], v[18:21]
	v_mfma_f32_16x16x32_bf16 v[6:9], v[146:149], v[202:205], v[6:9]
	v_mfma_f32_16x16x32_bf16 v[2:5], v[154:157], v[202:205], v[2:5]
	v_mfma_f32_16x16x32_bf16 v[54:57], v[150:153], v[166:169], v[54:57]
	v_mfma_f32_16x16x32_bf16 v[50:53], v[158:161], v[166:169], v[50:53]
	v_mfma_f32_16x16x32_bf16 v[38:41], v[150:153], v[174:177], v[38:41]
	v_mfma_f32_16x16x32_bf16 v[34:37], v[158:161], v[174:177], v[34:37]
	v_mfma_f32_16x16x32_bf16 v[22:25], v[150:153], v[198:201], v[22:25]
	v_mfma_f32_16x16x32_bf16 v[18:21], v[158:161], v[198:201], v[18:21]
	v_mfma_f32_16x16x32_bf16 v[6:9], v[150:153], v[212:215], v[6:9]
	v_mfma_f32_16x16x32_bf16 v[2:5], v[158:161], v[212:215], v[2:5]
	s_setprio 0
	s_barrier
	s_add_i32 s56, 0, 0x18000
	s_add_i32 s57, 0, 0x1c000
	v_add_u32_e32 v142, s56, v207
	v_add_u32_e32 v158, s57, v207
	ds_read_b128 v[130:133], v142
	ds_read_b128 v[134:137], v142 offset:1024
	ds_read_b128 v[138:141], v142 offset:2048
	ds_read_b128 v[142:145], v142 offset:3072
	ds_read_b128 v[146:149], v158
	ds_read_b128 v[150:153], v158 offset:1024
	ds_read_b128 v[154:157], v158 offset:2048
	ds_read_b128 v[158:161], v158 offset:3072
	s_add_u32 s34, s34, 0x40000
	s_addc_u32 s35, s35, 0
	s_mov_b32 m0, s41
	v_lshl_add_u64 v[224:225], s[34:35], 0, v[182:183]
	ds_read_b128 v[162:165], v211 offset:32768
	ds_read_b128 v[166:169], v211 offset:33792
	ds_read_b128 v[170:173], v211 offset:34816
	ds_read_b128 v[174:177], v211 offset:35840
	ds_read_b128 v[194:197], v211 offset:36864
	ds_read_b128 v[198:201], v211 offset:37888
	ds_read_b128 v[202:205], v211 offset:38912
	ds_read_b128 v[212:215], v211 offset:39936
	global_load_lds_dwordx4 v[224:225], off
	v_lshl_add_u64 v[224:225], s[34:35], 0, v[186:187]
	s_mov_b32 m0, s42
	s_nop 0
	global_load_lds_dwordx4 v[224:225], off
	s_waitcnt vmcnt(8)
	s_waitcnt lgkmcnt(0)
	s_barrier
	s_setprio 1
	s_waitcnt lgkmcnt(0)
	v_mfma_f32_16x16x32_bf16 v[126:129], v[130:133], v[162:165], v[126:129]
	v_mfma_f32_16x16x32_bf16 v[122:125], v[138:141], v[162:165], v[122:125]
	v_mfma_f32_16x16x32_bf16 v[110:113], v[130:133], v[170:173], v[110:113]
	v_mfma_f32_16x16x32_bf16 v[106:109], v[138:141], v[170:173], v[106:109]
	v_mfma_f32_16x16x32_bf16 v[94:97], v[130:133], v[194:197], v[94:97]
	v_mfma_f32_16x16x32_bf16 v[90:93], v[138:141], v[194:197], v[90:93]
	v_mfma_f32_16x16x32_bf16 v[78:81], v[130:133], v[202:205], v[78:81]
	v_mfma_f32_16x16x32_bf16 v[74:77], v[138:141], v[202:205], v[74:77]
	v_mfma_f32_16x16x32_bf16 v[126:129], v[134:137], v[166:169], v[126:129]
	v_mfma_f32_16x16x32_bf16 v[122:125], v[142:145], v[166:169], v[122:125]
	v_mfma_f32_16x16x32_bf16 v[110:113], v[134:137], v[174:177], v[110:113]
	v_mfma_f32_16x16x32_bf16 v[106:109], v[142:145], v[174:177], v[106:109]
	v_mfma_f32_16x16x32_bf16 v[94:97], v[134:137], v[198:201], v[94:97]
	v_mfma_f32_16x16x32_bf16 v[90:93], v[142:145], v[198:201], v[90:93]
	v_mfma_f32_16x16x32_bf16 v[78:81], v[134:137], v[212:215], v[78:81]
	v_mfma_f32_16x16x32_bf16 v[74:77], v[142:145], v[212:215], v[74:77]
	s_setprio 0
	s_setprio 1
	v_mfma_f32_16x16x32_bf16 v[118:121], v[146:149], v[162:165], v[118:121]
	v_mfma_f32_16x16x32_bf16 v[114:117], v[154:157], v[162:165], v[114:117]
	v_mfma_f32_16x16x32_bf16 v[102:105], v[146:149], v[170:173], v[102:105]
	v_mfma_f32_16x16x32_bf16 v[98:101], v[154:157], v[170:173], v[98:101]
	v_mfma_f32_16x16x32_bf16 v[86:89], v[146:149], v[194:197], v[86:89]
	v_mfma_f32_16x16x32_bf16 v[82:85], v[154:157], v[194:197], v[82:85]
	v_mfma_f32_16x16x32_bf16 v[70:73], v[146:149], v[202:205], v[70:73]
	v_mfma_f32_16x16x32_bf16 v[66:69], v[154:157], v[202:205], v[66:69]
	v_mfma_f32_16x16x32_bf16 v[118:121], v[150:153], v[166:169], v[118:121]
	v_mfma_f32_16x16x32_bf16 v[114:117], v[158:161], v[166:169], v[114:117]
	v_mfma_f32_16x16x32_bf16 v[102:105], v[150:153], v[174:177], v[102:105]
	v_mfma_f32_16x16x32_bf16 v[98:101], v[158:161], v[174:177], v[98:101]
	v_mfma_f32_16x16x32_bf16 v[86:89], v[150:153], v[198:201], v[86:89]
	v_mfma_f32_16x16x32_bf16 v[82:85], v[158:161], v[198:201], v[82:85]
	v_mfma_f32_16x16x32_bf16 v[70:73], v[150:153], v[212:215], v[70:73]
	v_mfma_f32_16x16x32_bf16 v[66:69], v[158:161], v[212:215], v[66:69]
	s_setprio 0
	s_barrier
	s_add_i32 s34, s56, s38
	v_lshl_add_u64 v[216:217], v[216:217], 0, s[22:23]
	s_mov_b32 m0, s34
	ds_read_b128 v[162:165], v211 offset:49152
	ds_read_b128 v[166:169], v211 offset:50176
	ds_read_b128 v[170:173], v211 offset:51200
	ds_read_b128 v[174:177], v211 offset:52224
	ds_read_b128 v[194:197], v211 offset:53248
	ds_read_b128 v[198:201], v211 offset:54272
	ds_read_b128 v[202:205], v211 offset:55296
	ds_read_b128 v[212:215], v211 offset:56320
	global_load_lds_dwordx4 v[216:217], off
	s_add_i32 m0, s34, 0x2000
	s_add_u32 s30, s30, 0x40080
	v_lshl_add_u64 v[216:217], v[218:219], 0, s[22:23]
	s_addc_u32 s31, s31, 0
	s_add_i32 s34, s57, s38
	global_load_lds_dwordx4 v[216:217], off
	v_lshl_add_u64 v[216:217], s[30:31], 0, v[184:185]
	s_mov_b32 m0, s34
	s_nop 0
	global_load_lds_dwordx4 v[216:217], off
	v_lshl_add_u64 v[216:217], s[30:31], 0, v[188:189]
	s_add_i32 m0, s34, 0x2000
	s_nop 0
	global_load_lds_dwordx4 v[216:217], off
	v_lshl_add_u64 v[216:217], v[220:221], 0, s[22:23]
	s_mov_b32 m0, s44
	s_nop 0
	global_load_lds_dwordx4 v[216:217], off
	v_lshl_add_u64 v[216:217], v[222:223], 0, s[22:23]
	s_mov_b32 m0, s45
	s_nop 0
	global_load_lds_dwordx4 v[216:217], off
	s_waitcnt vmcnt(8)
	s_waitcnt lgkmcnt(0)
	s_barrier
	s_setprio 1
	s_waitcnt lgkmcnt(0)
	v_mfma_f32_16x16x32_bf16 v[62:65], v[130:133], v[162:165], v[62:65]
	v_mfma_f32_16x16x32_bf16 v[58:61], v[138:141], v[162:165], v[58:61]
	v_mfma_f32_16x16x32_bf16 v[46:49], v[130:133], v[170:173], v[46:49]
	v_mfma_f32_16x16x32_bf16 v[42:45], v[138:141], v[170:173], v[42:45]
	v_mfma_f32_16x16x32_bf16 v[30:33], v[130:133], v[194:197], v[30:33]
	v_mfma_f32_16x16x32_bf16 v[26:29], v[138:141], v[194:197], v[26:29]
	v_mfma_f32_16x16x32_bf16 v[14:17], v[130:133], v[202:205], v[14:17]
	v_mfma_f32_16x16x32_bf16 v[10:13], v[138:141], v[202:205], v[10:13]
	v_mfma_f32_16x16x32_bf16 v[62:65], v[134:137], v[166:169], v[62:65]
	v_mfma_f32_16x16x32_bf16 v[58:61], v[142:145], v[166:169], v[58:61]
	v_mfma_f32_16x16x32_bf16 v[46:49], v[134:137], v[174:177], v[46:49]
	v_mfma_f32_16x16x32_bf16 v[42:45], v[142:145], v[174:177], v[42:45]
	v_mfma_f32_16x16x32_bf16 v[30:33], v[134:137], v[198:201], v[30:33]
	v_mfma_f32_16x16x32_bf16 v[26:29], v[142:145], v[198:201], v[26:29]
	v_mfma_f32_16x16x32_bf16 v[14:17], v[134:137], v[212:215], v[14:17]
	v_mfma_f32_16x16x32_bf16 v[10:13], v[142:145], v[212:215], v[10:13]
	s_setprio 0
	s_setprio 1
	v_mfma_f32_16x16x32_bf16 v[54:57], v[146:149], v[162:165], v[54:57]
	v_mfma_f32_16x16x32_bf16 v[50:53], v[154:157], v[162:165], v[50:53]
	v_mfma_f32_16x16x32_bf16 v[38:41], v[146:149], v[170:173], v[38:41]
	v_mfma_f32_16x16x32_bf16 v[34:37], v[154:157], v[170:173], v[34:37]
	v_mfma_f32_16x16x32_bf16 v[22:25], v[146:149], v[194:197], v[22:25]
	v_mfma_f32_16x16x32_bf16 v[18:21], v[154:157], v[194:197], v[18:21]
	v_mfma_f32_16x16x32_bf16 v[6:9], v[146:149], v[202:205], v[6:9]
	v_mfma_f32_16x16x32_bf16 v[2:5], v[154:157], v[202:205], v[2:5]
	v_mfma_f32_16x16x32_bf16 v[54:57], v[150:153], v[166:169], v[54:57]
	v_mfma_f32_16x16x32_bf16 v[50:53], v[158:161], v[166:169], v[50:53]
	v_mfma_f32_16x16x32_bf16 v[38:41], v[150:153], v[174:177], v[38:41]
	v_mfma_f32_16x16x32_bf16 v[34:37], v[158:161], v[174:177], v[34:37]
	v_mfma_f32_16x16x32_bf16 v[22:25], v[150:153], v[198:201], v[22:25]
	v_mfma_f32_16x16x32_bf16 v[18:21], v[158:161], v[198:201], v[18:21]
	v_mfma_f32_16x16x32_bf16 v[6:9], v[150:153], v[212:215], v[6:9]
	v_mfma_f32_16x16x32_bf16 v[2:5], v[158:161], v[212:215], v[2:5]
	s_setprio 0
	s_barrier
	s_add_i32 s55, s55, 2
	s_add_u32 s28, s28, 0x100
	s_addc_u32 s29, s29, 0
	s_add_u32 s53, s53, 0x100
	s_addc_u32 s54, s54, 0
	s_cmp_gt_u32 s55, 13
	s_cbranch_scc0 .LBB0_903
.Lpeel_x3:
	s_and_b64 vcc, exec, s[24:25]
	s_cbranch_vccz .LBB0_906
	s_barrier
.LBB0_906:
	v_lshl_add_u32 v196, s14, 8, v206
	v_lshl_or_b32 v194, s0, 8, v208
	v_ashrrev_i32_e32 v197, 31, v196
	v_ashrrev_i32_e32 v195, 31, v194
	v_lshlrev_b64 v[130:131], 12, v[196:197]
	v_lshl_add_u64 v[130:131], s[12:13], 0, v[130:131]
	v_lshlrev_b64 v[198:199], 2, v[194:195]
	v_lshl_add_u64 v[130:131], v[130:131], 0, v[198:199]
	global_load_dwordx4 v[216:219], v[130:131], off nt
	global_load_dwordx4 v[220:223], v[130:131], off offset:16 nt
	global_load_dwordx4 v[224:227], v[130:131], off offset:512 nt
	global_load_dwordx4 v[228:231], v[130:131], off offset:528 nt
	v_or_b32_e32 v204, 16, v196
	v_or_b32_e32 v202, 32, v196
	v_or_b32_e32 v200, 48, v196
	v_ashrrev_i32_e32 v205, 31, v204
	v_ashrrev_i32_e32 v203, 31, v202
	v_ashrrev_i32_e32 v201, 31, v200
	v_lshlrev_b64 v[130:131], 12, v[204:205]
	v_lshlrev_b64 v[132:133], 12, v[202:203]
	v_lshlrev_b64 v[134:135], 12, v[200:201]
	v_lshl_add_u64 v[130:131], s[12:13], 0, v[130:131]
	v_lshl_add_u64 v[132:133], s[12:13], 0, v[132:133]
	v_lshl_add_u64 v[134:135], s[12:13], 0, v[134:135]
	v_lshl_add_u64 v[130:131], v[130:131], 0, v[198:199]
	v_lshl_add_u64 v[132:133], v[132:133], 0, v[198:199]
	v_lshl_add_u64 v[134:135], v[134:135], 0, v[198:199]
	global_load_dwordx4 v[170:173], v[130:131], off offset:16 nt
	global_load_dwordx4 v[174:177], v[130:131], off nt
	global_load_dwordx4 v[162:165], v[130:131], off offset:528 nt
	global_load_dwordx4 v[166:169], v[130:131], off offset:512 nt
	global_load_dwordx4 v[154:157], v[132:133], off offset:16 nt
	global_load_dwordx4 v[158:161], v[132:133], off nt
	global_load_dwordx4 v[146:149], v[132:133], off offset:528 nt
	global_load_dwordx4 v[150:153], v[132:133], off offset:512 nt
	global_load_dwordx4 v[138:141], v[134:135], off offset:16 nt
	global_load_dwordx4 v[142:145], v[134:135], off nt
	s_nop 0
	global_load_dwordx4 v[130:133], v[134:135], off offset:528 nt
	s_nop 0
	global_load_dwordx4 v[134:137], v[134:135], off offset:512 nt
	v_and_b32_e32 v212, 64, v179
	v_xor_b32_e32 v213, 16, v179
	v_add_u32_e32 v212, 64, v212
	v_xor_b32_e32 v214, 32, v179
	v_cmp_lt_i32_e32 vcc, v213, v212
	v_lshlrev_b64 v[232:233], 11, v[196:197]
	s_lshl_b32 s28, s0, 2
	v_cndmask_b32_e32 v213, v179, v213, vcc
	v_cmp_lt_i32_e32 vcc, v214, v212
	s_ashr_i32 s29, s28, 31
	s_waitcnt vmcnt(0)
	v_pk_add_f32 v[128:129], v[128:129], v[218:219]
	v_cndmask_b32_e32 v215, v179, v214, vcc
	v_pk_add_f32 v[126:127], v[126:127], v[216:217]
	v_pk_add_f32 v[124:125], v[124:125], v[222:223]
	v_pk_add_f32 v[122:123], v[122:123], v[220:221]
	v_lshlrev_b32_e32 v214, 2, v213
	v_lshlrev_b32_e32 v213, 2, v215
	v_pk_add_f32 v[120:121], v[120:121], v[226:227]
	v_pk_add_f32 v[118:119], v[118:119], v[224:225]
	v_mul_f32_e32 v215, v127, v127
	v_mul_f32_e32 v220, v129, v129
	v_mul_f32_e32 v221, v123, v123
	v_mul_f32_e32 v222, v125, v125
	v_pk_add_f32 v[216:217], v[116:117], v[230:231]
	v_pk_add_f32 v[218:219], v[114:115], v[228:229]
	v_cvt_pk_bf16_f32 v116, v122, v123
	v_cvt_pk_bf16_f32 v117, v124, v125
	v_mul_f32_e32 v123, v119, v119
	v_mul_f32_e32 v125, v121, v121
	v_fmac_f32_e32 v215, v126, v126
	v_fmac_f32_e32 v220, v128, v128
	v_fmac_f32_e32 v221, v122, v122
	v_fmac_f32_e32 v222, v124, v124
	v_cvt_pk_bf16_f32 v114, v126, v127
	v_cvt_pk_bf16_f32 v115, v128, v129
	v_mul_f32_e32 v127, v219, v219
	v_mul_f32_e32 v129, v217, v217
	v_fmac_f32_e32 v123, v118, v118
	v_fmac_f32_e32 v125, v120, v120
	v_add_f32_e32 v122, v215, v220
	v_add_f32_e32 v124, v221, v222
	v_fmac_f32_e32 v127, v218, v218
	v_fmac_f32_e32 v129, v216, v216
	v_add_f32_e32 v123, v123, v125
	v_add_f32_e32 v122, v122, v124
	v_add_f32_e32 v122, v122, v123
	v_add_f32_e32 v123, v127, v129
	v_add_f32_e32 v124, v122, v123
	ds_bpermute_b32 v125, v214, v124
	v_lshl_add_u64 v[122:123], s[18:19], 0, v[232:233]
	v_lshl_add_u64 v[122:123], v[194:195], 1, v[122:123]
	global_store_dwordx4 v[122:123], v[114:117], off
	s_waitcnt lgkmcnt(0)
	s_nop 0
	v_add_f32_e32 v114, v124, v125
	ds_bpermute_b32 v115, v213, v114
	v_cvt_pk_bf16_f32 v116, v118, v119
	v_cvt_pk_bf16_f32 v117, v120, v121
	v_cvt_pk_bf16_f32 v118, v218, v219
	v_cvt_pk_bf16_f32 v119, v216, v217
	global_store_dwordx4 v[122:123], v[116:119], off offset:256
	s_and_saveexec_b64 s[30:31], s[6:7]
	s_cbranch_execz .LBB0_908
	v_lshlrev_b64 v[116:117], 6, v[196:197]
	v_lshl_add_u64 v[116:117], s[20:21], 0, v[116:117]
	v_lshl_add_u64 v[116:117], s[28:29], 2, v[116:117]
	s_lshl_b32 s14, s43, 2
	v_lshl_add_u64 v[116:117], v[116:117], 0, s[14:15]
	s_waitcnt lgkmcnt(0)
	v_add_f32_e32 v114, v114, v115
	global_store_dword v[116:117], v114, off

.LBB0_990:
	s_ashr_i32 s37, s36, 31
	s_lshl_b64 s[2:3], s[36:37], 19
	s_add_u32 s40, s48, s2
	s_addc_u32 s41, s49, s3
	s_and_b64 s[2:3], s[44:45], exec
	s_cselect_b32 s1, s41, s9
	s_cselect_b32 s2, s40, s8
	s_ashr_i32 s39, s38, 31
	s_lshl_b64 s[4:5], s[38:39], 19
	s_add_u32 s42, s50, s4
	s_addc_u32 s43, s51, s5
	s_and_b64 s[4:5], s[44:45], exec
	s_cselect_b32 s3, s43, s11
	s_cselect_b32 s4, s42, s10
	s_add_u32 s8, s8, 0x40080
	s_addc_u32 s9, s9, 0
	s_add_u32 s5, s10, 0x100
	s_addc_u32 s7, s11, 0
	s_mov_b32 s22, -2
	ds_read_b128 v[66:69], v219
	ds_read_b128 v[70:73], v219 offset:1024
	ds_read_b128 v[86:89], v219 offset:2048
	ds_read_b128 v[106:109], v219 offset:3072
	ds_read_b128 v[146:149], v220
	ds_read_b128 v[150:153], v220 offset:1024
	ds_read_b128 v[154:157], v220 offset:2048
	ds_read_b128 v[158:161], v220 offset:3072
	s_add_u32 s10, s8, 0xfffc0080
	s_addc_u32 s11, s9, -1
	s_cmp_eq_u32 s22, 12
	s_cselect_b32 s45, s1, s11
	s_cselect_b32 s44, s2, s10
	s_cselect_b32 s11, s3, s7
	s_cselect_b32 s10, s4, s5
	s_add_i32 m0, s54, 0xc000
	ds_read_b128 v[162:165], v221
	ds_read_b128 v[166:169], v221 offset:1024
	ds_read_b128 v[170:173], v221 offset:2048
	ds_read_b128 v[174:177], v221 offset:3072
	ds_read_b128 v[196:199], v221 offset:4096
	ds_read_b128 v[200:203], v221 offset:5120
	ds_read_b128 v[204:207], v221 offset:6144
	ds_read_b128 v[208:211], v221 offset:7168
	global_load_lds_dwordx4 v192, s[8:9]
	s_add_i32 m0, s54, 0xe000
	s_nop 0
	global_load_lds_dwordx4 v194, s[8:9]
	s_waitcnt vmcnt(8)
	s_waitcnt lgkmcnt(0)
	s_barrier
	s_setprio 1
	s_waitcnt lgkmcnt(0)
	v_mfma_f32_16x16x32_bf16 v[142:145], v[66:69], v[162:165], 0
	v_mfma_f32_16x16x32_bf16 v[134:137], v[86:89], v[162:165], 0
	v_mfma_f32_16x16x32_bf16 v[126:129], v[66:69], v[170:173], 0
	v_mfma_f32_16x16x32_bf16 v[122:125], v[86:89], v[170:173], 0
	v_mfma_f32_16x16x32_bf16 v[110:113], v[66:69], v[196:199], 0
	v_mfma_f32_16x16x32_bf16 v[102:105], v[86:89], v[196:199], 0
	v_mfma_f32_16x16x32_bf16 v[90:93], v[66:69], v[204:207], 0
	v_mfma_f32_16x16x32_bf16 v[82:85], v[86:89], v[204:207], 0
	v_mfma_f32_16x16x32_bf16 v[142:145], v[70:73], v[166:169], v[142:145]
	v_mfma_f32_16x16x32_bf16 v[134:137], v[106:109], v[166:169], v[134:137]
	v_mfma_f32_16x16x32_bf16 v[126:129], v[70:73], v[174:177], v[126:129]
	v_mfma_f32_16x16x32_bf16 v[122:125], v[106:109], v[174:177], v[122:125]
	v_mfma_f32_16x16x32_bf16 v[110:113], v[70:73], v[200:203], v[110:113]
	v_mfma_f32_16x16x32_bf16 v[102:105], v[106:109], v[200:203], v[102:105]
	v_mfma_f32_16x16x32_bf16 v[90:93], v[70:73], v[208:211], v[90:93]
	v_mfma_f32_16x16x32_bf16 v[82:85], v[106:109], v[208:211], v[82:85]
	s_setprio 0
	s_setprio 1
	v_mfma_f32_16x16x32_bf16 v[138:141], v[146:149], v[162:165], 0
	v_mfma_f32_16x16x32_bf16 v[130:133], v[154:157], v[162:165], 0
	v_mfma_f32_16x16x32_bf16 v[118:121], v[146:149], v[170:173], 0
	v_mfma_f32_16x16x32_bf16 v[114:117], v[154:157], v[170:173], 0
	v_mfma_f32_16x16x32_bf16 v[98:101], v[146:149], v[196:199], 0
	v_mfma_f32_16x16x32_bf16 v[94:97], v[154:157], v[196:199], 0
	v_mfma_f32_16x16x32_bf16 v[78:81], v[146:149], v[204:207], 0
	v_mfma_f32_16x16x32_bf16 v[74:77], v[154:157], v[204:207], 0
	v_mfma_f32_16x16x32_bf16 v[138:141], v[150:153], v[166:169], v[138:141]
	v_mfma_f32_16x16x32_bf16 v[130:133], v[158:161], v[166:169], v[130:133]
	v_mfma_f32_16x16x32_bf16 v[118:121], v[150:153], v[174:177], v[118:121]
	v_mfma_f32_16x16x32_bf16 v[114:117], v[158:161], v[174:177], v[114:117]
	v_mfma_f32_16x16x32_bf16 v[98:101], v[150:153], v[200:203], v[98:101]
	v_mfma_f32_16x16x32_bf16 v[94:97], v[158:161], v[200:203], v[94:97]
	v_mfma_f32_16x16x32_bf16 v[78:81], v[150:153], v[208:211], v[78:81]
	v_mfma_f32_16x16x32_bf16 v[74:77], v[158:161], v[208:211], v[74:77]
	s_setprio 0
	s_barrier
	s_add_i32 s37, s62, s53
	s_mov_b32 m0, s37
	ds_read_b128 v[162:165], v221 offset:16384
	ds_read_b128 v[166:169], v221 offset:17408
	ds_read_b128 v[170:173], v221 offset:18432
	ds_read_b128 v[174:177], v221 offset:19456
	ds_read_b128 v[196:199], v221 offset:20480
	ds_read_b128 v[200:203], v221 offset:21504
	ds_read_b128 v[204:207], v221 offset:22528
	ds_read_b128 v[208:211], v221 offset:23552
	global_load_lds_dwordx4 v184, s[10:11]
	s_add_i32 m0, s37, 0x2000
	s_add_u32 s46, s10, 0x40000
	s_addc_u32 s47, s11, 0
	s_add_i32 s37, s63, s53
	global_load_lds_dwordx4 v188, s[10:11]
	s_mov_b32 m0, s37
	s_nop 0
	global_load_lds_dwordx4 v184, s[46:47]
	s_add_i32 m0, s37, 0x2000
	s_nop 0
	global_load_lds_dwordx4 v188, s[46:47]
	s_mov_b32 m0, s54
	s_nop 0
	global_load_lds_dwordx4 v182, s[44:45]
	s_mov_b32 m0, s55
	s_nop 0
	global_load_lds_dwordx4 v186, s[44:45]
	s_waitcnt vmcnt(8)
	s_waitcnt lgkmcnt(0)
	s_barrier
	s_setprio 1
	s_waitcnt lgkmcnt(0)
	v_mfma_f32_16x16x32_bf16 v[62:65], v[66:69], v[162:165], 0
	v_mfma_f32_16x16x32_bf16 v[54:57], v[86:89], v[162:165], 0
	v_mfma_f32_16x16x32_bf16 v[46:49], v[66:69], v[170:173], 0
	v_mfma_f32_16x16x32_bf16 v[42:45], v[86:89], v[170:173], 0
	v_mfma_f32_16x16x32_bf16 v[30:33], v[66:69], v[196:199], 0
	v_mfma_f32_16x16x32_bf16 v[26:29], v[86:89], v[196:199], 0
	v_mfma_f32_16x16x32_bf16 v[14:17], v[66:69], v[204:207], 0
	v_mfma_f32_16x16x32_bf16 v[10:13], v[86:89], v[204:207], 0
	v_mfma_f32_16x16x32_bf16 v[62:65], v[70:73], v[166:169], v[62:65]
	v_mfma_f32_16x16x32_bf16 v[54:57], v[106:109], v[166:169], v[54:57]
	v_mfma_f32_16x16x32_bf16 v[46:49], v[70:73], v[174:177], v[46:49]
	v_mfma_f32_16x16x32_bf16 v[42:45], v[106:109], v[174:177], v[42:45]
	v_mfma_f32_16x16x32_bf16 v[30:33], v[70:73], v[200:203], v[30:33]
	v_mfma_f32_16x16x32_bf16 v[26:29], v[106:109], v[200:203], v[26:29]
	v_mfma_f32_16x16x32_bf16 v[14:17], v[70:73], v[208:211], v[14:17]
	v_mfma_f32_16x16x32_bf16 v[10:13], v[106:109], v[208:211], v[10:13]
	s_setprio 0
	s_setprio 1
	v_mfma_f32_16x16x32_bf16 v[58:61], v[146:149], v[162:165], 0
	v_mfma_f32_16x16x32_bf16 v[50:53], v[154:157], v[162:165], 0
	v_mfma_f32_16x16x32_bf16 v[38:41], v[146:149], v[170:173], 0
	v_mfma_f32_16x16x32_bf16 v[34:37], v[154:157], v[170:173], 0
	v_mfma_f32_16x16x32_bf16 v[22:25], v[146:149], v[196:199], 0
	v_mfma_f32_16x16x32_bf16 v[18:21], v[154:157], v[196:199], 0
	v_mfma_f32_16x16x32_bf16 v[6:9], v[146:149], v[204:207], 0
	v_mfma_f32_16x16x32_bf16 v[2:5], v[154:157], v[204:207], 0
	v_mfma_f32_16x16x32_bf16 v[58:61], v[150:153], v[166:169], v[58:61]
	v_mfma_f32_16x16x32_bf16 v[50:53], v[158:161], v[166:169], v[50:53]
	v_mfma_f32_16x16x32_bf16 v[38:41], v[150:153], v[174:177], v[38:41]
	v_mfma_f32_16x16x32_bf16 v[34:37], v[158:161], v[174:177], v[34:37]
	v_mfma_f32_16x16x32_bf16 v[22:25], v[150:153], v[200:203], v[22:25]
	v_mfma_f32_16x16x32_bf16 v[18:21], v[158:161], v[200:203], v[18:21]
	v_mfma_f32_16x16x32_bf16 v[6:9], v[150:153], v[208:211], v[6:9]
	v_mfma_f32_16x16x32_bf16 v[2:5], v[158:161], v[208:211], v[2:5]
	s_setprio 0
	s_barrier
	s_add_i32 s37, 0, 0x18000
	s_add_i32 s39, 0, 0x1c000
	v_add_u32_e32 v106, s37, v213
	v_add_u32_e32 v158, s39, v213
	ds_read_b128 v[66:69], v106
	ds_read_b128 v[70:73], v106 offset:1024
	ds_read_b128 v[86:89], v106 offset:2048
	ds_read_b128 v[106:109], v106 offset:3072
	ds_read_b128 v[146:149], v158
	ds_read_b128 v[150:153], v158 offset:1024
	ds_read_b128 v[154:157], v158 offset:2048
	ds_read_b128 v[158:161], v158 offset:3072
	s_add_u32 s44, s44, 0x40000
	s_addc_u32 s45, s45, 0
	s_mov_b32 m0, s56
	ds_read_b128 v[162:165], v221 offset:32768
	ds_read_b128 v[166:169], v221 offset:33792
	ds_read_b128 v[170:173], v221 offset:34816
	ds_read_b128 v[174:177], v221 offset:35840
	ds_read_b128 v[196:199], v221 offset:36864
	ds_read_b128 v[200:203], v221 offset:37888
	ds_read_b128 v[204:207], v221 offset:38912
	ds_read_b128 v[208:211], v221 offset:39936
	global_load_lds_dwordx4 v182, s[44:45]
	s_mov_b32 m0, s57
	s_nop 0
	global_load_lds_dwordx4 v186, s[44:45]
	s_waitcnt vmcnt(8)
	s_waitcnt lgkmcnt(0)
	s_barrier
	s_setprio 1
	s_waitcnt lgkmcnt(0)
	v_mfma_f32_16x16x32_bf16 v[142:145], v[66:69], v[162:165], v[142:145]
	v_mfma_f32_16x16x32_bf16 v[134:137], v[86:89], v[162:165], v[134:137]
	v_mfma_f32_16x16x32_bf16 v[126:129], v[66:69], v[170:173], v[126:129]
	v_mfma_f32_16x16x32_bf16 v[122:125], v[86:89], v[170:173], v[122:125]
	v_mfma_f32_16x16x32_bf16 v[110:113], v[66:69], v[196:199], v[110:113]
	v_mfma_f32_16x16x32_bf16 v[102:105], v[86:89], v[196:199], v[102:105]
	v_mfma_f32_16x16x32_bf16 v[90:93], v[66:69], v[204:207], v[90:93]
	v_mfma_f32_16x16x32_bf16 v[82:85], v[86:89], v[204:207], v[82:85]
	v_mfma_f32_16x16x32_bf16 v[142:145], v[70:73], v[166:169], v[142:145]
	v_mfma_f32_16x16x32_bf16 v[134:137], v[106:109], v[166:169], v[134:137]
	v_mfma_f32_16x16x32_bf16 v[126:129], v[70:73], v[174:177], v[126:129]
	v_mfma_f32_16x16x32_bf16 v[122:125], v[106:109], v[174:177], v[122:125]
	v_mfma_f32_16x16x32_bf16 v[110:113], v[70:73], v[200:203], v[110:113]
	v_mfma_f32_16x16x32_bf16 v[102:105], v[106:109], v[200:203], v[102:105]
	v_mfma_f32_16x16x32_bf16 v[90:93], v[70:73], v[208:211], v[90:93]
	v_mfma_f32_16x16x32_bf16 v[82:85], v[106:109], v[208:211], v[82:85]
	s_setprio 0
	s_setprio 1
	v_mfma_f32_16x16x32_bf16 v[138:141], v[146:149], v[162:165], v[138:141]
	v_mfma_f32_16x16x32_bf16 v[130:133], v[154:157], v[162:165], v[130:133]
	v_mfma_f32_16x16x32_bf16 v[118:121], v[146:149], v[170:173], v[118:121]
	v_mfma_f32_16x16x32_bf16 v[114:117], v[154:157], v[170:173], v[114:117]
	v_mfma_f32_16x16x32_bf16 v[98:101], v[146:149], v[196:199], v[98:101]
	v_mfma_f32_16x16x32_bf16 v[94:97], v[154:157], v[196:199], v[94:97]
	v_mfma_f32_16x16x32_bf16 v[78:81], v[146:149], v[204:207], v[78:81]
	v_mfma_f32_16x16x32_bf16 v[74:77], v[154:157], v[204:207], v[74:77]
	v_mfma_f32_16x16x32_bf16 v[138:141], v[150:153], v[166:169], v[138:141]
	v_mfma_f32_16x16x32_bf16 v[130:133], v[158:161], v[166:169], v[130:133]
	v_mfma_f32_16x16x32_bf16 v[118:121], v[150:153], v[174:177], v[118:121]
	v_mfma_f32_16x16x32_bf16 v[114:117], v[158:161], v[174:177], v[114:117]
	v_mfma_f32_16x16x32_bf16 v[98:101], v[150:153], v[200:203], v[98:101]
	v_mfma_f32_16x16x32_bf16 v[94:97], v[158:161], v[200:203], v[94:97]
	v_mfma_f32_16x16x32_bf16 v[78:81], v[150:153], v[208:211], v[78:81]
	v_mfma_f32_16x16x32_bf16 v[74:77], v[158:161], v[208:211], v[74:77]
	s_setprio 0
	s_barrier
	s_add_i32 s37, s37, s53
	s_mov_b32 m0, s37
	ds_read_b128 v[162:165], v221 offset:49152
	ds_read_b128 v[166:169], v221 offset:50176
	ds_read_b128 v[170:173], v221 offset:51200
	ds_read_b128 v[174:177], v221 offset:52224
	ds_read_b128 v[196:199], v221 offset:53248
	ds_read_b128 v[200:203], v221 offset:54272
	ds_read_b128 v[204:207], v221 offset:55296
	ds_read_b128 v[208:211], v221 offset:56320
	s_add_u32 s98, s10, 0x80
	s_addc_u32 s99, s11, 0
	global_load_lds_dwordx4 v184, s[98:99]
	s_add_i32 m0, s37, 0x2000
	s_add_u32 s10, s10, 0x40080
	s_addc_u32 s11, s11, 0
	s_add_i32 s37, s39, s53
	global_load_lds_dwordx4 v188, s[98:99]
	s_mov_b32 m0, s37
	s_nop 0
	global_load_lds_dwordx4 v184, s[10:11]
	s_add_i32 m0, s37, 0x2000
	s_nop 0
	global_load_lds_dwordx4 v188, s[10:11]
	s_add_u32 s98, s44, 0xfffc0080
	s_addc_u32 s99, s45, -1
	s_mov_b32 m0, s60
	s_nop 0
	global_load_lds_dwordx4 v182, s[98:99]
	s_mov_b32 m0, s61
	s_nop 0
	global_load_lds_dwordx4 v186, s[98:99]
	s_waitcnt vmcnt(8)
	s_waitcnt lgkmcnt(0)
	s_barrier
	s_setprio 1
	s_waitcnt lgkmcnt(0)
	v_mfma_f32_16x16x32_bf16 v[62:65], v[66:69], v[162:165], v[62:65]
	v_mfma_f32_16x16x32_bf16 v[54:57], v[86:89], v[162:165], v[54:57]
	v_mfma_f32_16x16x32_bf16 v[46:49], v[66:69], v[170:173], v[46:49]
	v_mfma_f32_16x16x32_bf16 v[42:45], v[86:89], v[170:173], v[42:45]
	v_mfma_f32_16x16x32_bf16 v[30:33], v[66:69], v[196:199], v[30:33]
	v_mfma_f32_16x16x32_bf16 v[26:29], v[86:89], v[196:199], v[26:29]
	v_mfma_f32_16x16x32_bf16 v[14:17], v[66:69], v[204:207], v[14:17]
	v_mfma_f32_16x16x32_bf16 v[10:13], v[86:89], v[204:207], v[10:13]
	v_mfma_f32_16x16x32_bf16 v[62:65], v[70:73], v[166:169], v[62:65]
	v_mfma_f32_16x16x32_bf16 v[54:57], v[106:109], v[166:169], v[54:57]
	v_mfma_f32_16x16x32_bf16 v[46:49], v[70:73], v[174:177], v[46:49]
	v_mfma_f32_16x16x32_bf16 v[42:45], v[106:109], v[174:177], v[42:45]
	v_mfma_f32_16x16x32_bf16 v[30:33], v[70:73], v[200:203], v[30:33]
	v_mfma_f32_16x16x32_bf16 v[26:29], v[106:109], v[200:203], v[26:29]
	v_mfma_f32_16x16x32_bf16 v[14:17], v[70:73], v[208:211], v[14:17]
	v_mfma_f32_16x16x32_bf16 v[10:13], v[106:109], v[208:211], v[10:13]
	s_setprio 0
	s_setprio 1
	v_mfma_f32_16x16x32_bf16 v[58:61], v[146:149], v[162:165], v[58:61]
	v_mfma_f32_16x16x32_bf16 v[50:53], v[154:157], v[162:165], v[50:53]
	v_mfma_f32_16x16x32_bf16 v[38:41], v[146:149], v[170:173], v[38:41]
	v_mfma_f32_16x16x32_bf16 v[34:37], v[154:157], v[170:173], v[34:37]
	v_mfma_f32_16x16x32_bf16 v[22:25], v[146:149], v[196:199], v[22:25]
	v_mfma_f32_16x16x32_bf16 v[18:21], v[154:157], v[196:199], v[18:21]
	v_mfma_f32_16x16x32_bf16 v[6:9], v[146:149], v[204:207], v[6:9]
	v_mfma_f32_16x16x32_bf16 v[2:5], v[154:157], v[204:207], v[2:5]
	v_mfma_f32_16x16x32_bf16 v[58:61], v[150:153], v[166:169], v[58:61]
	v_mfma_f32_16x16x32_bf16 v[50:53], v[158:161], v[166:169], v[50:53]
	v_mfma_f32_16x16x32_bf16 v[38:41], v[150:153], v[174:177], v[38:41]
	v_mfma_f32_16x16x32_bf16 v[34:37], v[158:161], v[174:177], v[34:37]
	v_mfma_f32_16x16x32_bf16 v[22:25], v[150:153], v[200:203], v[22:25]
	v_mfma_f32_16x16x32_bf16 v[18:21], v[158:161], v[200:203], v[18:21]
	v_mfma_f32_16x16x32_bf16 v[6:9], v[150:153], v[208:211], v[6:9]
	v_mfma_f32_16x16x32_bf16 v[2:5], v[158:161], v[208:211], v[2:5]
	s_setprio 0
	s_barrier
	s_add_i32 s22, s22, 2
	s_add_u32 s8, s8, 0x100
	s_addc_u32 s9, s9, 0
	s_add_u32 s5, s5, 0x100
	s_addc_u32 s7, s7, 0
	s_cmp_gt_u32 s22, 13
	s_cbranch_scc1 .Lpeel_x4
.LBB0_991:
	ds_read_b128 v[66:69], v219
	ds_read_b128 v[70:73], v219 offset:1024
	ds_read_b128 v[86:89], v219 offset:2048
	ds_read_b128 v[106:109], v219 offset:3072
	ds_read_b128 v[146:149], v220
	ds_read_b128 v[150:153], v220 offset:1024
	ds_read_b128 v[154:157], v220 offset:2048
	ds_read_b128 v[158:161], v220 offset:3072
	s_add_u32 s10, s8, 0xfffc0080
	s_addc_u32 s11, s9, -1
	s_cmp_eq_u32 s22, 12
	s_cselect_b32 s45, s1, s11
	s_cselect_b32 s44, s2, s10
	s_cselect_b32 s11, s3, s7
	s_cselect_b32 s10, s4, s5
	s_add_i32 m0, s54, 0xc000
	ds_read_b128 v[162:165], v221
	ds_read_b128 v[166:169], v221 offset:1024
	ds_read_b128 v[170:173], v221 offset:2048
	ds_read_b128 v[174:177], v221 offset:3072
	ds_read_b128 v[196:199], v221 offset:4096
	ds_read_b128 v[200:203], v221 offset:5120
	ds_read_b128 v[204:207], v221 offset:6144
	ds_read_b128 v[208:211], v221 offset:7168
	global_load_lds_dwordx4 v192, s[8:9]
	s_add_i32 m0, s54, 0xe000
	s_nop 0
	global_load_lds_dwordx4 v194, s[8:9]
	s_waitcnt vmcnt(8)
	s_waitcnt lgkmcnt(0)
	s_barrier
	s_setprio 1
	s_waitcnt lgkmcnt(0)
	v_mfma_f32_16x16x32_bf16 v[142:145], v[66:69], v[162:165], v[142:145]
	v_mfma_f32_16x16x32_bf16 v[134:137], v[86:89], v[162:165], v[134:137]
	v_mfma_f32_16x16x32_bf16 v[126:129], v[66:69], v[170:173], v[126:129]
	v_mfma_f32_16x16x32_bf16 v[122:125], v[86:89], v[170:173], v[122:125]
	v_mfma_f32_16x16x32_bf16 v[110:113], v[66:69], v[196:199], v[110:113]
	v_mfma_f32_16x16x32_bf16 v[102:105], v[86:89], v[196:199], v[102:105]
	v_mfma_f32_16x16x32_bf16 v[90:93], v[66:69], v[204:207], v[90:93]
	v_mfma_f32_16x16x32_bf16 v[82:85], v[86:89], v[204:207], v[82:85]
	v_mfma_f32_16x16x32_bf16 v[142:145], v[70:73], v[166:169], v[142:145]
	v_mfma_f32_16x16x32_bf16 v[134:137], v[106:109], v[166:169], v[134:137]
	v_mfma_f32_16x16x32_bf16 v[126:129], v[70:73], v[174:177], v[126:129]
	v_mfma_f32_16x16x32_bf16 v[122:125], v[106:109], v[174:177], v[122:125]
	v_mfma_f32_16x16x32_bf16 v[110:113], v[70:73], v[200:203], v[110:113]
	v_mfma_f32_16x16x32_bf16 v[102:105], v[106:109], v[200:203], v[102:105]
	v_mfma_f32_16x16x32_bf16 v[90:93], v[70:73], v[208:211], v[90:93]
	v_mfma_f32_16x16x32_bf16 v[82:85], v[106:109], v[208:211], v[82:85]
	s_setprio 0
	s_setprio 1
	v_mfma_f32_16x16x32_bf16 v[138:141], v[146:149], v[162:165], v[138:141]
	v_mfma_f32_16x16x32_bf16 v[130:133], v[154:157], v[162:165], v[130:133]
	v_mfma_f32_16x16x32_bf16 v[118:121], v[146:149], v[170:173], v[118:121]
	v_mfma_f32_16x16x32_bf16 v[114:117], v[154:157], v[170:173], v[114:117]
	v_mfma_f32_16x16x32_bf16 v[98:101], v[146:149], v[196:199], v[98:101]
	v_mfma_f32_16x16x32_bf16 v[94:97], v[154:157], v[196:199], v[94:97]
	v_mfma_f32_16x16x32_bf16 v[78:81], v[146:149], v[204:207], v[78:81]
	v_mfma_f32_16x16x32_bf16 v[74:77], v[154:157], v[204:207], v[74:77]
	v_mfma_f32_16x16x32_bf16 v[138:141], v[150:153], v[166:169], v[138:141]
	v_mfma_f32_16x16x32_bf16 v[130:133], v[158:161], v[166:169], v[130:133]
	v_mfma_f32_16x16x32_bf16 v[118:121], v[150:153], v[174:177], v[118:121]
	v_mfma_f32_16x16x32_bf16 v[114:117], v[158:161], v[174:177], v[114:117]
	v_mfma_f32_16x16x32_bf16 v[98:101], v[150:153], v[200:203], v[98:101]
	v_mfma_f32_16x16x32_bf16 v[94:97], v[158:161], v[200:203], v[94:97]
	v_mfma_f32_16x16x32_bf16 v[78:81], v[150:153], v[208:211], v[78:81]
	v_mfma_f32_16x16x32_bf16 v[74:77], v[158:161], v[208:211], v[74:77]
	s_setprio 0
	s_barrier
	s_add_i32 s37, s62, s53
	s_mov_b32 m0, s37
	ds_read_b128 v[162:165], v221 offset:16384
	ds_read_b128 v[166:169], v221 offset:17408
	ds_read_b128 v[170:173], v221 offset:18432
	ds_read_b128 v[174:177], v221 offset:19456
	ds_read_b128 v[196:199], v221 offset:20480
	ds_read_b128 v[200:203], v221 offset:21504
	ds_read_b128 v[204:207], v221 offset:22528
	ds_read_b128 v[208:211], v221 offset:23552
	global_load_lds_dwordx4 v184, s[10:11]
	s_add_i32 m0, s37, 0x2000
	s_add_u32 s46, s10, 0x40000
	s_addc_u32 s47, s11, 0
	s_add_i32 s37, s63, s53
	global_load_lds_dwordx4 v188, s[10:11]
	s_mov_b32 m0, s37
	s_nop 0
	global_load_lds_dwordx4 v184, s[46:47]
	s_add_i32 m0, s37, 0x2000
	s_nop 0
	global_load_lds_dwordx4 v188, s[46:47]
	s_mov_b32 m0, s54
	s_nop 0
	global_load_lds_dwordx4 v182, s[44:45]
	s_mov_b32 m0, s55
	s_nop 0
	global_load_lds_dwordx4 v186, s[44:45]
	s_waitcnt vmcnt(8)
	s_waitcnt lgkmcnt(0)
	s_barrier
	s_setprio 1
	s_waitcnt lgkmcnt(0)
	v_mfma_f32_16x16x32_bf16 v[62:65], v[66:69], v[162:165], v[62:65]
	v_mfma_f32_16x16x32_bf16 v[54:57], v[86:89], v[162:165], v[54:57]
	v_mfma_f32_16x16x32_bf16 v[46:49], v[66:69], v[170:173], v[46:49]
	v_mfma_f32_16x16x32_bf16 v[42:45], v[86:89], v[170:173], v[42:45]
	v_mfma_f32_16x16x32_bf16 v[30:33], v[66:69], v[196:199], v[30:33]
	v_mfma_f32_16x16x32_bf16 v[26:29], v[86:89], v[196:199], v[26:29]
	v_mfma_f32_16x16x32_bf16 v[14:17], v[66:69], v[204:207], v[14:17]
	v_mfma_f32_16x16x32_bf16 v[10:13], v[86:89], v[204:207], v[10:13]
	v_mfma_f32_16x16x32_bf16 v[62:65], v[70:73], v[166:169], v[62:65]
	v_mfma_f32_16x16x32_bf16 v[54:57], v[106:109], v[166:169], v[54:57]
	v_mfma_f32_16x16x32_bf16 v[46:49], v[70:73], v[174:177], v[46:49]
	v_mfma_f32_16x16x32_bf16 v[42:45], v[106:109], v[174:177], v[42:45]
	v_mfma_f32_16x16x32_bf16 v[30:33], v[70:73], v[200:203], v[30:33]
	v_mfma_f32_16x16x32_bf16 v[26:29], v[106:109], v[200:203], v[26:29]
	v_mfma_f32_16x16x32_bf16 v[14:17], v[70:73], v[208:211], v[14:17]
	v_mfma_f32_16x16x32_bf16 v[10:13], v[106:109], v[208:211], v[10:13]
	s_setprio 0
	s_setprio 1
	v_mfma_f32_16x16x32_bf16 v[58:61], v[146:149], v[162:165], v[58:61]
	v_mfma_f32_16x16x32_bf16 v[50:53], v[154:157], v[162:165], v[50:53]
	v_mfma_f32_16x16x32_bf16 v[38:41], v[146:149], v[170:173], v[38:41]
	v_mfma_f32_16x16x32_bf16 v[34:37], v[154:157], v[170:173], v[34:37]
	v_mfma_f32_16x16x32_bf16 v[22:25], v[146:149], v[196:199], v[22:25]
	v_mfma_f32_16x16x32_bf16 v[18:21], v[154:157], v[196:199], v[18:21]
	v_mfma_f32_16x16x32_bf16 v[6:9], v[146:149], v[204:207], v[6:9]
	v_mfma_f32_16x16x32_bf16 v[2:5], v[154:157], v[204:207], v[2:5]
	v_mfma_f32_16x16x32_bf16 v[58:61], v[150:153], v[166:169], v[58:61]
	v_mfma_f32_16x16x32_bf16 v[50:53], v[158:161], v[166:169], v[50:53]
	v_mfma_f32_16x16x32_bf16 v[38:41], v[150:153], v[174:177], v[38:41]
	v_mfma_f32_16x16x32_bf16 v[34:37], v[158:161], v[174:177], v[34:37]
	v_mfma_f32_16x16x32_bf16 v[22:25], v[150:153], v[200:203], v[22:25]
	v_mfma_f32_16x16x32_bf16 v[18:21], v[158:161], v[200:203], v[18:21]
	v_mfma_f32_16x16x32_bf16 v[6:9], v[150:153], v[208:211], v[6:9]
	v_mfma_f32_16x16x32_bf16 v[2:5], v[158:161], v[208:211], v[2:5]
	s_setprio 0
	s_barrier
	s_add_i32 s37, 0, 0x18000
	s_add_i32 s39, 0, 0x1c000
	v_add_u32_e32 v106, s37, v213
	v_add_u32_e32 v158, s39, v213
	ds_read_b128 v[66:69], v106
	ds_read_b128 v[70:73], v106 offset:1024
	ds_read_b128 v[86:89], v106 offset:2048
	ds_read_b128 v[106:109], v106 offset:3072
	ds_read_b128 v[146:149], v158
	ds_read_b128 v[150:153], v158 offset:1024
	ds_read_b128 v[154:157], v158 offset:2048
	ds_read_b128 v[158:161], v158 offset:3072
	s_add_u32 s44, s44, 0x40000
	s_addc_u32 s45, s45, 0
	s_mov_b32 m0, s56
	ds_read_b128 v[162:165], v221 offset:32768
	ds_read_b128 v[166:169], v221 offset:33792
	ds_read_b128 v[170:173], v221 offset:34816
	ds_read_b128 v[174:177], v221 offset:35840
	ds_read_b128 v[196:199], v221 offset:36864
	ds_read_b128 v[200:203], v221 offset:37888
	ds_read_b128 v[204:207], v221 offset:38912
	ds_read_b128 v[208:211], v221 offset:39936
	global_load_lds_dwordx4 v182, s[44:45]
	s_mov_b32 m0, s57
	s_nop 0
	global_load_lds_dwordx4 v186, s[44:45]
	s_waitcnt vmcnt(8)
	s_waitcnt lgkmcnt(0)
	s_barrier
	s_setprio 1
	s_waitcnt lgkmcnt(0)
	v_mfma_f32_16x16x32_bf16 v[142:145], v[66:69], v[162:165], v[142:145]
	v_mfma_f32_16x16x32_bf16 v[134:137], v[86:89], v[162:165], v[134:137]
	v_mfma_f32_16x16x32_bf16 v[126:129], v[66:69], v[170:173], v[126:129]
	v_mfma_f32_16x16x32_bf16 v[122:125], v[86:89], v[170:173], v[122:125]
	v_mfma_f32_16x16x32_bf16 v[110:113], v[66:69], v[196:199], v[110:113]
	v_mfma_f32_16x16x32_bf16 v[102:105], v[86:89], v[196:199], v[102:105]
	v_mfma_f32_16x16x32_bf16 v[90:93], v[66:69], v[204:207], v[90:93]
	v_mfma_f32_16x16x32_bf16 v[82:85], v[86:89], v[204:207], v[82:85]
	v_mfma_f32_16x16x32_bf16 v[142:145], v[70:73], v[166:169], v[142:145]
	v_mfma_f32_16x16x32_bf16 v[134:137], v[106:109], v[166:169], v[134:137]
	v_mfma_f32_16x16x32_bf16 v[126:129], v[70:73], v[174:177], v[126:129]
	v_mfma_f32_16x16x32_bf16 v[122:125], v[106:109], v[174:177], v[122:125]
	v_mfma_f32_16x16x32_bf16 v[110:113], v[70:73], v[200:203], v[110:113]
	v_mfma_f32_16x16x32_bf16 v[102:105], v[106:109], v[200:203], v[102:105]
	v_mfma_f32_16x16x32_bf16 v[90:93], v[70:73], v[208:211], v[90:93]
	v_mfma_f32_16x16x32_bf16 v[82:85], v[106:109], v[208:211], v[82:85]
	s_setprio 0
	s_setprio 1
	v_mfma_f32_16x16x32_bf16 v[138:141], v[146:149], v[162:165], v[138:141]
	v_mfma_f32_16x16x32_bf16 v[130:133], v[154:157], v[162:165], v[130:133]
	v_mfma_f32_16x16x32_bf16 v[118:121], v[146:149], v[170:173], v[118:121]
	v_mfma_f32_16x16x32_bf16 v[114:117], v[154:157], v[170:173], v[114:117]
	v_mfma_f32_16x16x32_bf16 v[98:101], v[146:149], v[196:199], v[98:101]
	v_mfma_f32_16x16x32_bf16 v[94:97], v[154:157], v[196:199], v[94:97]
	v_mfma_f32_16x16x32_bf16 v[78:81], v[146:149], v[204:207], v[78:81]
	v_mfma_f32_16x16x32_bf16 v[74:77], v[154:157], v[204:207], v[74:77]
	v_mfma_f32_16x16x32_bf16 v[138:141], v[150:153], v[166:169], v[138:141]
	v_mfma_f32_16x16x32_bf16 v[130:133], v[158:161], v[166:169], v[130:133]
	v_mfma_f32_16x16x32_bf16 v[118:121], v[150:153], v[174:177], v[118:121]
	v_mfma_f32_16x16x32_bf16 v[114:117], v[158:161], v[174:177], v[114:117]
	v_mfma_f32_16x16x32_bf16 v[98:101], v[150:153], v[200:203], v[98:101]
	v_mfma_f32_16x16x32_bf16 v[94:97], v[158:161], v[200:203], v[94:97]
	v_mfma_f32_16x16x32_bf16 v[78:81], v[150:153], v[208:211], v[78:81]
	v_mfma_f32_16x16x32_bf16 v[74:77], v[158:161], v[208:211], v[74:77]
	s_setprio 0
	s_barrier
	s_add_i32 s37, s37, s53
	s_mov_b32 m0, s37
	ds_read_b128 v[162:165], v221 offset:49152
	ds_read_b128 v[166:169], v221 offset:50176
	ds_read_b128 v[170:173], v221 offset:51200
	ds_read_b128 v[174:177], v221 offset:52224
	ds_read_b128 v[196:199], v221 offset:53248
	ds_read_b128 v[200:203], v221 offset:54272
	ds_read_b128 v[204:207], v221 offset:55296
	ds_read_b128 v[208:211], v221 offset:56320
	s_add_u32 s98, s10, 0x80
	s_addc_u32 s99, s11, 0
	global_load_lds_dwordx4 v184, s[98:99]
	s_add_i32 m0, s37, 0x2000
	s_add_u32 s10, s10, 0x40080
	s_addc_u32 s11, s11, 0
	s_add_i32 s37, s39, s53
	global_load_lds_dwordx4 v188, s[98:99]
	s_mov_b32 m0, s37
	s_nop 0
	global_load_lds_dwordx4 v184, s[10:11]
	s_add_i32 m0, s37, 0x2000
	s_nop 0
	global_load_lds_dwordx4 v188, s[10:11]
	s_add_u32 s98, s44, 0xfffc0080
	s_addc_u32 s99, s45, -1
	s_mov_b32 m0, s60
	s_nop 0
	global_load_lds_dwordx4 v182, s[98:99]
	s_mov_b32 m0, s61
	s_nop 0
	global_load_lds_dwordx4 v186, s[98:99]
	s_waitcnt vmcnt(8)
	s_waitcnt lgkmcnt(0)
	s_barrier
	s_setprio 1
	s_waitcnt lgkmcnt(0)
	v_mfma_f32_16x16x32_bf16 v[62:65], v[66:69], v[162:165], v[62:65]
	v_mfma_f32_16x16x32_bf16 v[54:57], v[86:89], v[162:165], v[54:57]
	v_mfma_f32_16x16x32_bf16 v[46:49], v[66:69], v[170:173], v[46:49]
	v_mfma_f32_16x16x32_bf16 v[42:45], v[86:89], v[170:173], v[42:45]
	v_mfma_f32_16x16x32_bf16 v[30:33], v[66:69], v[196:199], v[30:33]
	v_mfma_f32_16x16x32_bf16 v[26:29], v[86:89], v[196:199], v[26:29]
	v_mfma_f32_16x16x32_bf16 v[14:17], v[66:69], v[204:207], v[14:17]
	v_mfma_f32_16x16x32_bf16 v[10:13], v[86:89], v[204:207], v[10:13]
	v_mfma_f32_16x16x32_bf16 v[62:65], v[70:73], v[166:169], v[62:65]
	v_mfma_f32_16x16x32_bf16 v[54:57], v[106:109], v[166:169], v[54:57]
	v_mfma_f32_16x16x32_bf16 v[46:49], v[70:73], v[174:177], v[46:49]
	v_mfma_f32_16x16x32_bf16 v[42:45], v[106:109], v[174:177], v[42:45]
	v_mfma_f32_16x16x32_bf16 v[30:33], v[70:73], v[200:203], v[30:33]
	v_mfma_f32_16x16x32_bf16 v[26:29], v[106:109], v[200:203], v[26:29]
	v_mfma_f32_16x16x32_bf16 v[14:17], v[70:73], v[208:211], v[14:17]
	v_mfma_f32_16x16x32_bf16 v[10:13], v[106:109], v[208:211], v[10:13]
	s_setprio 0
	s_setprio 1
	v_mfma_f32_16x16x32_bf16 v[58:61], v[146:149], v[162:165], v[58:61]
	v_mfma_f32_16x16x32_bf16 v[50:53], v[154:157], v[162:165], v[50:53]
	v_mfma_f32_16x16x32_bf16 v[38:41], v[146:149], v[170:173], v[38:41]
	v_mfma_f32_16x16x32_bf16 v[34:37], v[154:157], v[170:173], v[34:37]
	v_mfma_f32_16x16x32_bf16 v[22:25], v[146:149], v[196:199], v[22:25]
	v_mfma_f32_16x16x32_bf16 v[18:21], v[154:157], v[196:199], v[18:21]
	v_mfma_f32_16x16x32_bf16 v[6:9], v[146:149], v[204:207], v[6:9]
	v_mfma_f32_16x16x32_bf16 v[2:5], v[154:157], v[204:207], v[2:5]
	v_mfma_f32_16x16x32_bf16 v[58:61], v[150:153], v[166:169], v[58:61]
	v_mfma_f32_16x16x32_bf16 v[50:53], v[158:161], v[166:169], v[50:53]
	v_mfma_f32_16x16x32_bf16 v[38:41], v[150:153], v[174:177], v[38:41]
	v_mfma_f32_16x16x32_bf16 v[34:37], v[158:161], v[174:177], v[34:37]
	v_mfma_f32_16x16x32_bf16 v[22:25], v[150:153], v[200:203], v[22:25]
	v_mfma_f32_16x16x32_bf16 v[18:21], v[158:161], v[200:203], v[18:21]
	v_mfma_f32_16x16x32_bf16 v[6:9], v[150:153], v[208:211], v[6:9]
	v_mfma_f32_16x16x32_bf16 v[2:5], v[158:161], v[208:211], v[2:5]
	s_setprio 0
	s_barrier
	s_add_i32 s22, s22, 2
	s_add_u32 s8, s8, 0x100
	s_addc_u32 s9, s9, 0
	s_add_u32 s5, s5, 0x100
	s_addc_u32 s7, s7, 0
	s_cmp_gt_u32 s22, 13
	s_cbranch_scc0 .LBB0_991
.Lpeel_x4:
	s_and_b64 vcc, exec, s[30:31]
	s_cbranch_vccz .LBB0_994

.LBB0_1107:
	s_and_b64 s[20:21], s[26:27], exec
	s_cselect_b32 s21, s35, s23
	s_cselect_b32 s20, s34, s22
	s_add_u32 s22, s22, 0xb0080
	s_addc_u32 s23, s23, 0
	s_add_u32 s49, s24, 0x100
	s_addc_u32 s50, s25, 0
	s_mov_b32 s51, -2
	ds_read_b128 v[142:145], v150
	ds_read_b128 v[156:159], v150 offset:1024
	ds_read_b128 v[160:163], v150 offset:2048
	ds_read_b128 v[164:167], v150 offset:3072
	ds_read_b128 v[168:171], v151
	ds_read_b128 v[172:175], v151 offset:1024
	ds_read_b128 v[180:183], v151 offset:2048
	ds_read_b128 v[184:187], v151 offset:3072
	s_add_u32 s24, s22, 0xfff50080
	s_addc_u32 s25, s23, -1
	s_cmp_eq_u32 s51, 40
	s_cselect_b32 s27, s21, s25
	s_cselect_b32 s26, s20, s24
	s_cselect_b32 s25, s19, s50
	s_cselect_b32 s24, s18, s49
	s_mov_b32 m0, s36
	ds_read_b128 v[188:191], v152
	ds_read_b128 v[192:195], v152 offset:1024
	ds_read_b128 v[196:199], v152 offset:2048
	ds_read_b128 v[200:203], v152 offset:3072
	ds_read_b128 v[204:207], v152 offset:4096
	ds_read_b128 v[208:211], v152 offset:5120
	ds_read_b128 v[212:215], v152 offset:6144
	ds_read_b128 v[216:219], v152 offset:7168
	global_load_lds_dwordx4 v138, s[22:23]
	s_mov_b32 m0, s37
	s_nop 0
	global_load_lds_dwordx4 v140, s[22:23]
	s_waitcnt vmcnt(8)
	s_waitcnt lgkmcnt(0)
	s_barrier
	s_setprio 1
	s_waitcnt lgkmcnt(0)
	v_mfma_f32_16x16x32_bf16 v[126:129], v[142:145], v[188:191], 0
	v_mfma_f32_16x16x32_bf16 v[122:125], v[160:163], v[188:191], 0
	v_mfma_f32_16x16x32_bf16 v[110:113], v[142:145], v[196:199], 0
	v_mfma_f32_16x16x32_bf16 v[106:109], v[160:163], v[196:199], 0
	v_mfma_f32_16x16x32_bf16 v[94:97], v[142:145], v[204:207], 0
	v_mfma_f32_16x16x32_bf16 v[90:93], v[160:163], v[204:207], 0
	v_mfma_f32_16x16x32_bf16 v[78:81], v[142:145], v[212:215], 0
	v_mfma_f32_16x16x32_bf16 v[74:77], v[160:163], v[212:215], 0
	v_mfma_f32_16x16x32_bf16 v[126:129], v[156:159], v[192:195], v[126:129]
	v_mfma_f32_16x16x32_bf16 v[122:125], v[164:167], v[192:195], v[122:125]
	v_mfma_f32_16x16x32_bf16 v[110:113], v[156:159], v[200:203], v[110:113]
	v_mfma_f32_16x16x32_bf16 v[106:109], v[164:167], v[200:203], v[106:109]
	v_mfma_f32_16x16x32_bf16 v[94:97], v[156:159], v[208:211], v[94:97]
	v_mfma_f32_16x16x32_bf16 v[90:93], v[164:167], v[208:211], v[90:93]
	v_mfma_f32_16x16x32_bf16 v[78:81], v[156:159], v[216:219], v[78:81]
	v_mfma_f32_16x16x32_bf16 v[74:77], v[164:167], v[216:219], v[74:77]
	s_setprio 0
	s_setprio 1
	v_mfma_f32_16x16x32_bf16 v[118:121], v[168:171], v[188:191], 0
	v_mfma_f32_16x16x32_bf16 v[114:117], v[180:183], v[188:191], 0
	v_mfma_f32_16x16x32_bf16 v[102:105], v[168:171], v[196:199], 0
	v_mfma_f32_16x16x32_bf16 v[98:101], v[180:183], v[196:199], 0
	v_mfma_f32_16x16x32_bf16 v[86:89], v[168:171], v[204:207], 0
	v_mfma_f32_16x16x32_bf16 v[82:85], v[180:183], v[204:207], 0
	v_mfma_f32_16x16x32_bf16 v[70:73], v[168:171], v[212:215], 0
	v_mfma_f32_16x16x32_bf16 v[66:69], v[180:183], v[212:215], 0
	v_mfma_f32_16x16x32_bf16 v[118:121], v[172:175], v[192:195], v[118:121]
	v_mfma_f32_16x16x32_bf16 v[114:117], v[184:187], v[192:195], v[114:117]
	v_mfma_f32_16x16x32_bf16 v[102:105], v[172:175], v[200:203], v[102:105]
	v_mfma_f32_16x16x32_bf16 v[98:101], v[184:187], v[200:203], v[98:101]
	v_mfma_f32_16x16x32_bf16 v[86:89], v[172:175], v[208:211], v[86:89]
	v_mfma_f32_16x16x32_bf16 v[82:85], v[184:187], v[208:211], v[82:85]
	v_mfma_f32_16x16x32_bf16 v[70:73], v[172:175], v[216:219], v[70:73]
	v_mfma_f32_16x16x32_bf16 v[66:69], v[184:187], v[216:219], v[66:69]
	s_setprio 0
	s_barrier
	s_mov_b32 m0, s38
	s_add_u32 s52, s24, 0xb0000
	ds_read_b128 v[188:191], v152 offset:16384
	ds_read_b128 v[192:195], v152 offset:17408
	ds_read_b128 v[196:199], v152 offset:18432
	ds_read_b128 v[200:203], v152 offset:19456
	ds_read_b128 v[204:207], v152 offset:20480
	ds_read_b128 v[208:211], v152 offset:21504
	ds_read_b128 v[212:215], v152 offset:22528
	ds_read_b128 v[216:219], v152 offset:23552
	global_load_lds_dwordx4 v134, s[24:25]
	s_mov_b32 m0, s39
	s_addc_u32 s53, s25, 0
	global_load_lds_dwordx4 v130, s[24:25]
	s_mov_b32 m0, s40
	s_nop 0
	global_load_lds_dwordx4 v134, s[52:53]
	s_mov_b32 m0, s41
	s_nop 0
	global_load_lds_dwordx4 v130, s[52:53]
	s_mov_b32 m0, s4
	s_nop 0
	global_load_lds_dwordx4 v136, s[26:27]
	s_mov_b32 m0, s5
	s_nop 0
	global_load_lds_dwordx4 v132, s[26:27]
	s_waitcnt vmcnt(8)
	s_waitcnt lgkmcnt(0)
	s_barrier
	s_setprio 1
	s_waitcnt lgkmcnt(0)
	v_mfma_f32_16x16x32_bf16 v[62:65], v[142:145], v[188:191], 0
	v_mfma_f32_16x16x32_bf16 v[58:61], v[160:163], v[188:191], 0
	v_mfma_f32_16x16x32_bf16 v[46:49], v[142:145], v[196:199], 0
	v_mfma_f32_16x16x32_bf16 v[42:45], v[160:163], v[196:199], 0
	v_mfma_f32_16x16x32_bf16 v[34:37], v[142:145], v[204:207], 0
	v_mfma_f32_16x16x32_bf16 v[26:29], v[160:163], v[204:207], 0
	v_mfma_f32_16x16x32_bf16 v[18:21], v[142:145], v[212:215], 0
	v_mfma_f32_16x16x32_bf16 v[10:13], v[160:163], v[212:215], 0
	v_mfma_f32_16x16x32_bf16 v[62:65], v[156:159], v[192:195], v[62:65]
	v_mfma_f32_16x16x32_bf16 v[58:61], v[164:167], v[192:195], v[58:61]
	v_mfma_f32_16x16x32_bf16 v[46:49], v[156:159], v[200:203], v[46:49]
	v_mfma_f32_16x16x32_bf16 v[42:45], v[164:167], v[200:203], v[42:45]
	v_mfma_f32_16x16x32_bf16 v[34:37], v[156:159], v[208:211], v[34:37]
	v_mfma_f32_16x16x32_bf16 v[26:29], v[164:167], v[208:211], v[26:29]
	v_mfma_f32_16x16x32_bf16 v[18:21], v[156:159], v[216:219], v[18:21]
	v_mfma_f32_16x16x32_bf16 v[10:13], v[164:167], v[216:219], v[10:13]
	s_setprio 0
	s_setprio 1
	v_mfma_f32_16x16x32_bf16 v[54:57], v[168:171], v[188:191], 0
	v_mfma_f32_16x16x32_bf16 v[50:53], v[180:183], v[188:191], 0
	v_mfma_f32_16x16x32_bf16 v[38:41], v[168:171], v[196:199], 0
	v_mfma_f32_16x16x32_bf16 v[30:33], v[180:183], v[196:199], 0
	v_mfma_f32_16x16x32_bf16 v[22:25], v[168:171], v[204:207], 0
	v_mfma_f32_16x16x32_bf16 v[14:17], v[180:183], v[204:207], 0
	v_mfma_f32_16x16x32_bf16 v[6:9], v[168:171], v[212:215], 0
	v_mfma_f32_16x16x32_bf16 v[2:5], v[180:183], v[212:215], 0
	v_mfma_f32_16x16x32_bf16 v[54:57], v[172:175], v[192:195], v[54:57]
	v_mfma_f32_16x16x32_bf16 v[50:53], v[184:187], v[192:195], v[50:53]
	v_mfma_f32_16x16x32_bf16 v[38:41], v[172:175], v[200:203], v[38:41]
	v_mfma_f32_16x16x32_bf16 v[30:33], v[184:187], v[200:203], v[30:33]
	v_mfma_f32_16x16x32_bf16 v[22:25], v[172:175], v[208:211], v[22:25]
	v_mfma_f32_16x16x32_bf16 v[14:17], v[184:187], v[208:211], v[14:17]
	v_mfma_f32_16x16x32_bf16 v[6:9], v[172:175], v[216:219], v[6:9]
	v_mfma_f32_16x16x32_bf16 v[2:5], v[184:187], v[216:219], v[2:5]
	s_setprio 0
	s_barrier
	ds_read_b128 v[142:145], v153
	ds_read_b128 v[156:159], v153 offset:1024
	ds_read_b128 v[160:163], v153 offset:2048
	ds_read_b128 v[164:167], v153 offset:3072
	ds_read_b128 v[168:171], v154
	ds_read_b128 v[172:175], v154 offset:1024
	ds_read_b128 v[180:183], v154 offset:2048
	ds_read_b128 v[184:187], v154 offset:3072
	s_add_u32 s26, s26, 0xb0000
	s_addc_u32 s27, s27, 0
	s_mov_b32 m0, s29
	ds_read_b128 v[188:191], v152 offset:32768
	ds_read_b128 v[192:195], v152 offset:33792
	ds_read_b128 v[196:199], v152 offset:34816
	ds_read_b128 v[200:203], v152 offset:35840
	ds_read_b128 v[204:207], v152 offset:36864
	ds_read_b128 v[208:211], v152 offset:37888
	ds_read_b128 v[212:215], v152 offset:38912
	ds_read_b128 v[216:219], v152 offset:39936
	global_load_lds_dwordx4 v136, s[26:27]
	s_mov_b32 m0, s30
	s_nop 0
	global_load_lds_dwordx4 v132, s[26:27]
	s_waitcnt vmcnt(8)
	s_waitcnt lgkmcnt(0)
	s_barrier
	s_setprio 1
	s_waitcnt lgkmcnt(0)
	v_mfma_f32_16x16x32_bf16 v[126:129], v[142:145], v[188:191], v[126:129]
	v_mfma_f32_16x16x32_bf16 v[122:125], v[160:163], v[188:191], v[122:125]
	v_mfma_f32_16x16x32_bf16 v[110:113], v[142:145], v[196:199], v[110:113]
	v_mfma_f32_16x16x32_bf16 v[106:109], v[160:163], v[196:199], v[106:109]
	v_mfma_f32_16x16x32_bf16 v[94:97], v[142:145], v[204:207], v[94:97]
	v_mfma_f32_16x16x32_bf16 v[90:93], v[160:163], v[204:207], v[90:93]
	v_mfma_f32_16x16x32_bf16 v[78:81], v[142:145], v[212:215], v[78:81]
	v_mfma_f32_16x16x32_bf16 v[74:77], v[160:163], v[212:215], v[74:77]
	v_mfma_f32_16x16x32_bf16 v[126:129], v[156:159], v[192:195], v[126:129]
	v_mfma_f32_16x16x32_bf16 v[122:125], v[164:167], v[192:195], v[122:125]
	v_mfma_f32_16x16x32_bf16 v[110:113], v[156:159], v[200:203], v[110:113]
	v_mfma_f32_16x16x32_bf16 v[106:109], v[164:167], v[200:203], v[106:109]
	v_mfma_f32_16x16x32_bf16 v[94:97], v[156:159], v[208:211], v[94:97]
	v_mfma_f32_16x16x32_bf16 v[90:93], v[164:167], v[208:211], v[90:93]
	v_mfma_f32_16x16x32_bf16 v[78:81], v[156:159], v[216:219], v[78:81]
	v_mfma_f32_16x16x32_bf16 v[74:77], v[164:167], v[216:219], v[74:77]
	s_setprio 0
	s_setprio 1
	v_mfma_f32_16x16x32_bf16 v[118:121], v[168:171], v[188:191], v[118:121]
	v_mfma_f32_16x16x32_bf16 v[114:117], v[180:183], v[188:191], v[114:117]
	v_mfma_f32_16x16x32_bf16 v[102:105], v[168:171], v[196:199], v[102:105]
	v_mfma_f32_16x16x32_bf16 v[98:101], v[180:183], v[196:199], v[98:101]
	v_mfma_f32_16x16x32_bf16 v[86:89], v[168:171], v[204:207], v[86:89]
	v_mfma_f32_16x16x32_bf16 v[82:85], v[180:183], v[204:207], v[82:85]
	v_mfma_f32_16x16x32_bf16 v[70:73], v[168:171], v[212:215], v[70:73]
	v_mfma_f32_16x16x32_bf16 v[66:69], v[180:183], v[212:215], v[66:69]
	v_mfma_f32_16x16x32_bf16 v[118:121], v[172:175], v[192:195], v[118:121]
	v_mfma_f32_16x16x32_bf16 v[114:117], v[184:187], v[192:195], v[114:117]
	v_mfma_f32_16x16x32_bf16 v[102:105], v[172:175], v[200:203], v[102:105]
	v_mfma_f32_16x16x32_bf16 v[98:101], v[184:187], v[200:203], v[98:101]
	v_mfma_f32_16x16x32_bf16 v[86:89], v[172:175], v[208:211], v[86:89]
	v_mfma_f32_16x16x32_bf16 v[82:85], v[184:187], v[208:211], v[82:85]
	v_mfma_f32_16x16x32_bf16 v[70:73], v[172:175], v[216:219], v[70:73]
	v_mfma_f32_16x16x32_bf16 v[66:69], v[184:187], v[216:219], v[66:69]
	s_setprio 0
	s_barrier
	s_mov_b32 m0, s42
	ds_read_b128 v[188:191], v152 offset:49152
	ds_read_b128 v[192:195], v152 offset:50176
	ds_read_b128 v[196:199], v152 offset:51200
	ds_read_b128 v[200:203], v152 offset:52224
	ds_read_b128 v[204:207], v152 offset:53248
	ds_read_b128 v[208:211], v152 offset:54272
	ds_read_b128 v[212:215], v152 offset:55296
	ds_read_b128 v[216:219], v152 offset:56320
	s_add_u32 s98, s24, 0x80
	s_addc_u32 s99, s25, 0
	global_load_lds_dwordx4 v134, s[98:99]
	s_mov_b32 m0, s43
	s_add_u32 s24, s24, 0xb0080
	s_addc_u32 s25, s25, 0
	global_load_lds_dwordx4 v130, s[98:99]
	s_mov_b32 m0, s44
	s_nop 0
	global_load_lds_dwordx4 v134, s[24:25]
	s_mov_b32 m0, s45
	s_nop 0
	global_load_lds_dwordx4 v130, s[24:25]
	s_add_u32 s98, s26, 0xfff50080
	s_addc_u32 s99, s27, -1
	s_mov_b32 m0, s0
	s_nop 0
	global_load_lds_dwordx4 v136, s[98:99]
	s_mov_b32 m0, s1
	s_nop 0
	global_load_lds_dwordx4 v132, s[98:99]
	s_waitcnt vmcnt(8)
	s_waitcnt lgkmcnt(0)
	s_barrier
	s_setprio 1
	s_waitcnt lgkmcnt(0)
	v_mfma_f32_16x16x32_bf16 v[62:65], v[142:145], v[188:191], v[62:65]
	v_mfma_f32_16x16x32_bf16 v[58:61], v[160:163], v[188:191], v[58:61]
	v_mfma_f32_16x16x32_bf16 v[46:49], v[142:145], v[196:199], v[46:49]
	v_mfma_f32_16x16x32_bf16 v[42:45], v[160:163], v[196:199], v[42:45]
	v_mfma_f32_16x16x32_bf16 v[34:37], v[142:145], v[204:207], v[34:37]
	v_mfma_f32_16x16x32_bf16 v[26:29], v[160:163], v[204:207], v[26:29]
	v_mfma_f32_16x16x32_bf16 v[18:21], v[142:145], v[212:215], v[18:21]
	v_mfma_f32_16x16x32_bf16 v[10:13], v[160:163], v[212:215], v[10:13]
	v_mfma_f32_16x16x32_bf16 v[62:65], v[156:159], v[192:195], v[62:65]
	v_mfma_f32_16x16x32_bf16 v[58:61], v[164:167], v[192:195], v[58:61]
	v_mfma_f32_16x16x32_bf16 v[46:49], v[156:159], v[200:203], v[46:49]
	v_mfma_f32_16x16x32_bf16 v[42:45], v[164:167], v[200:203], v[42:45]
	v_mfma_f32_16x16x32_bf16 v[34:37], v[156:159], v[208:211], v[34:37]
	v_mfma_f32_16x16x32_bf16 v[26:29], v[164:167], v[208:211], v[26:29]
	v_mfma_f32_16x16x32_bf16 v[18:21], v[156:159], v[216:219], v[18:21]
	v_mfma_f32_16x16x32_bf16 v[10:13], v[164:167], v[216:219], v[10:13]
	s_setprio 0
	s_setprio 1
	v_mfma_f32_16x16x32_bf16 v[54:57], v[168:171], v[188:191], v[54:57]
	v_mfma_f32_16x16x32_bf16 v[50:53], v[180:183], v[188:191], v[50:53]
	v_mfma_f32_16x16x32_bf16 v[38:41], v[168:171], v[196:199], v[38:41]
	v_mfma_f32_16x16x32_bf16 v[30:33], v[180:183], v[196:199], v[30:33]
	v_mfma_f32_16x16x32_bf16 v[22:25], v[168:171], v[204:207], v[22:25]
	v_mfma_f32_16x16x32_bf16 v[14:17], v[180:183], v[204:207], v[14:17]
	v_mfma_f32_16x16x32_bf16 v[6:9], v[168:171], v[212:215], v[6:9]
	v_mfma_f32_16x16x32_bf16 v[2:5], v[180:183], v[212:215], v[2:5]
	v_mfma_f32_16x16x32_bf16 v[54:57], v[172:175], v[192:195], v[54:57]
	v_mfma_f32_16x16x32_bf16 v[50:53], v[184:187], v[192:195], v[50:53]
	v_mfma_f32_16x16x32_bf16 v[38:41], v[172:175], v[200:203], v[38:41]
	v_mfma_f32_16x16x32_bf16 v[30:33], v[184:187], v[200:203], v[30:33]
	v_mfma_f32_16x16x32_bf16 v[22:25], v[172:175], v[208:211], v[22:25]
	v_mfma_f32_16x16x32_bf16 v[14:17], v[184:187], v[208:211], v[14:17]
	v_mfma_f32_16x16x32_bf16 v[6:9], v[172:175], v[216:219], v[6:9]
	v_mfma_f32_16x16x32_bf16 v[2:5], v[184:187], v[216:219], v[2:5]
	s_setprio 0
	s_barrier
	s_add_i32 s51, s51, 2
	s_add_u32 s22, s22, 0x100
	s_addc_u32 s23, s23, 0
	s_add_u32 s49, s49, 0x100
	s_addc_u32 s50, s50, 0
	s_cmp_gt_u32 s51, 41
	s_cbranch_scc1 .Lpeel_x5

.Lpeel_x5:
	s_and_b64 vcc, exec, s[16:17]
	s_cbranch_vccz .LBB0_1111
	s_barrier
